# SwiGLU epilogues (P4,P10): row-rms loads hoisted+prefetched one unit ahead, cross-lane reduce; vgpr 256
# speedup vs baseline: 1.0287x; 1.0184x over previous
; #define PG8_STAGE(bufoff, gbase, voff) do { _Pragma("unroll") for (int _i = 0; _i < 2; ++_i) \
;         __builtin_amdgcn_global_load_lds((const unsigned*)((const char*)(gbase) + (voff)[_i]), (PG8_LAS unsigned*)(lds + (bufoff) + ldsw + _i * 8192), 16, 0, 0); } while (0)
; #define PG8_WAIT_V(n) asm volatile("s_waitcnt vmcnt(" #n ")" ::: "memory")
; #define PG8_BAR __builtin_amdgcn_s_barrier()
; template <class Epi, class Sched, bool ALIGN_EPI = false, bool SP2 = false>
; __device__ __forceinline__ void gemm_phase(PG8_LAS unsigned char* lds, const Gemm g, const Sched& S, const Epi& E) {
;     ...
;     const char* cA = (const char*)g.A + (size_t)cur.pm * tstep + (size_t)cur.kt0 * kstep; const char* cB = (const char*)g.Bt + (size_t)cur.pn * tstep + (size_t)cur.kt0 * kstep;
;     S.a_ready(cur);
;     if constexpr (SP2) {
;         PG8_STAGE(PG8_SB(0, 0), cB, voffB); PG8_STAGE(PG8_SB(0, 1), cB + hstep, voffB); PG8_STAGE(PG8_SA(0, 0), cA, voffA); PG8_STAGE(PG8_SA(0, 1), cA + hstep, voffA);
;         if (wr == 1) PG8_BAR;
;         PG8_WAIT_V(2); PG8_BAR;
;         PG8_STAGE(PG8_SB(1, 0), cB + kstep, voffB); PG8_STAGE(PG8_SA(1, 0), cA + kstep, voffA); PG8_STAGE(PG8_SB(1, 1), cB + hstep + kstep, voffB);
;         PG8_WAIT_V(6); PG8_BAR;
; __device__ __forceinline__ float row_rs(const float* part, int row) {
;     const f32x4* p = (const f32x4*)(part + (size_t)row * 16);
;     const f32x4 a = p[0], b = p[1], c = p[2], d = p[3];
.LBB0_569:
	v_and_b32_e32 v246, 15, v146
	v_lshrrev_b32_e32 v192, 8, v146
	v_lshl_or_b32 v246, v192, 6, v246
	v_bfe_u32 v192, v146, 4, 2
	v_lshlrev_b32_e32 v192, 4, v192
	v_lshl_or_b32 v246, v246, 6, v192
	v_lshl_add_u32 v192, s30, 14, v246
	v_add_u32_e32 v193, 0x2000, v192
	global_load_dwordx4 v[222:225], v192, s[90:91]
	global_load_dwordx4 v[226:229], v192, s[90:91] offset:1024
	global_load_dwordx4 v[230:233], v192, s[90:91] offset:2048
	global_load_dwordx4 v[234:237], v192, s[90:91] offset:3072
	global_load_dwordx4 v[238:241], v193, s[90:91]
	global_load_dwordx4 v[242:245], v193, s[90:91] offset:1024
	global_load_dwordx4 v[248:251], v193, s[90:91] offset:2048
	global_load_dwordx4 v[252:255], v193, s[90:91] offset:3072
	s_add_u32 s33, s74, 0x800000
	s_addc_u32 s46, s75, 0
	s_ashr_i32 s31, s30, 31
	s_lshl_b64 s[0:1], s[30:31], 19
	s_add_u32 s34, s88, s0
	s_addc_u32 s35, s89, s1
	s_ashr_i32 s29, s28, 31
	v_lshrrev_b32_e32 v4, 1, v146
	s_lshl_b64 s[0:1], s[28:29], 19
	v_and_b32_e32 v10, 24, v4
	v_lshrrev_b32_e32 v4, 5, v146
	s_add_u32 s36, s33, s0
	v_and_b32_e32 v4, 4, v4
	v_bfe_u32 v5, v146, 2, 2
	s_addc_u32 s37, s46, s1
	v_lshlrev_b32_e32 v1, 4, v146
	v_and_b32_e32 v2, 32, v146
	v_bfe_u32 v3, v146, 2, 4
	v_or3_b32 v4, v4, v5, v10
	v_lshrrev_b32_e32 v5, 3, v146
	s_movk_i32 s1, 0x70
	v_bitop3_b32 v2, v1, v2, 48 bitop3:0x6c
	v_and_or_b32 v6, v5, s1, v3
	s_movk_i32 s1, 0x60
	v_add_u32_e32 v1, 0x2000, v1
	v_and_or_b32 v5, v5, s1, v4
	v_lshrrev_b32_e32 v1, 7, v1
	s_movk_i32 s1, 0xf0
	v_and_or_b32 v3, v1, s1, v3
	s_movk_i32 s1, 0xe0
	v_and_or_b32 v1, v1, s1, v4
	s_lshr_b32 s1, s4, 6
	s_lshl_b32 s29, s1, 10
	v_and_or_b32 v2, v146, 64, v2
	s_add_i32 s31, s29, 0
	v_lshl_or_b32 v132, v5, 11, v2
	s_add_i32 m0, s31, 0x10000
	s_lshr_b32 s0, s4, 8
	global_load_lds_dwordx4 v132, s[36:37]
	s_add_i32 m0, s31, 0x12000
	v_lshl_or_b32 v136, v1, 11, v2
	s_add_u32 s2, s36, 0x40000
	global_load_lds_dwordx4 v136, s[36:37]
	s_addc_u32 s3, s37, 0
	s_add_i32 m0, s31, 0x14000
	s_add_i32 s47, s31, 0x2000
	global_load_lds_dwordx4 v132, s[2:3]
	s_add_i32 m0, s31, 0x16000
	v_lshl_or_b32 v130, v6, 11, v2
	global_load_lds_dwordx4 v136, s[2:3]
	s_mov_b32 m0, s31
	s_add_u32 s2, s34, 0x40000
	v_lshl_or_b32 v134, v3, 11, v2
	global_load_lds_dwordx4 v130, s[34:35]
	s_mov_b32 m0, s47
	s_addc_u32 s3, s35, 0
	s_add_i32 s48, s31, 0x4000
	global_load_lds_dwordx4 v134, s[34:35]
	s_mov_b32 m0, s48
	s_add_i32 s49, s31, 0x6000
	global_load_lds_dwordx4 v130, s[2:3]
	s_mov_b32 m0, s49
	v_mov_b32_e32 v133, 0
	global_load_lds_dwordx4 v134, s[2:3]
	v_mov_b32_e32 v137, v133
	v_mov_b32_e32 v131, v133
	v_mov_b32_e32 v135, v133
	s_cmp_eq_u32 s0, 1
	s_mov_b32 s11, 0
	v_lshl_add_u64 v[8:9], s[36:37], 0, v[132:133]
	v_lshl_add_u64 v[6:7], s[36:37], 0, v[136:137]
	v_lshl_add_u64 v[2:3], s[34:35], 0, v[130:131]
	s_cselect_b64 s[12:13], -1, 0
	s_cmp_lg_u32 s0, 1
	v_lshl_add_u64 v[4:5], s[34:35], 0, v[134:135]
	s_cbranch_scc1 .LBB0_571
	s_barrier

; __device__ __forceinline__ float silu_f(float x) { return x * __builtin_amdgcn_rcpf(1.0f + __expf(-x)); }
; __device__ __forceinline__ u32x4 pack8(const f32x4 a, const f32x4 b) { u32x4 w; w.x = cvt_pk_bf16(a[0], a[1]); w.y = cvt_pk_bf16(a[2], a[3]); w.z = cvt_pk_bf16(b[0], b[1]); w.w = cvt_pk_bf16(b[2], b[3]); return w; }
; __device__ __forceinline__ float row_rs(const float* part, int row) {
;     const f32x4* p = (const f32x4*)(part + (size_t)row * 16);
;     const f32x4 a = p[0], b = p[1], c = p[2], d = p[3];
;     const float s = (((a[0] + a[1]) + (a[2] + a[3])) + ((b[0] + b[1]) + (b[2] + b[3]))) + (((c[0] + c[1]) + (c[2] + c[3])) + ((d[0] + d[1]) + (d[2] + d[3])));
;     return rsqrtf(s * (1.0f / D) + RMS_EPS);
; }
;     __device__ __forceinline__ void operator()(const Acc& acc, const pg8::Unit& u, int wr, int wc, int fr, int fq) const {
;     ...
;         for (int ai = 0; ai < 2; ++ai)
; #pragma unroll
;             for (int m = 0; m < 4; ++m) {
;                 const int row = u.pm * 256 + ai * 128 + wr * 64 + m * 16 + fr;
;                 const float rs = row_rs(part, row);
;                 const int col = u.pn * 128 + wc * 32 + 8 * fq;
;                 f32x4 h[2];
; #pragma unroll
;                 for (int n = 0; n < 2; ++n)
; #pragma unroll
;                     for (int e = 0; e < 4; ++e) h[n][e] = silu_f(acc[ai][0][m][n][e] * rs) * (acc[ai][1][m][n][e] * rs);
;                 *(u32x4*)(hff + (size_t)row * DFF + col) = pack8(h[0], h[1]);
.LBB0_596:
	s_waitcnt vmcnt(8)
	v_add_f32_e32 v222, v222, v223
	v_add_f32_e32 v224, v224, v225
	v_add_f32_e32 v226, v226, v227
	v_add_f32_e32 v228, v228, v229
	v_add_f32_e32 v230, v230, v231
	v_add_f32_e32 v232, v232, v233
	v_add_f32_e32 v234, v234, v235
	v_add_f32_e32 v236, v236, v237
	v_add_f32_e32 v238, v238, v239
	v_add_f32_e32 v240, v240, v241
	v_add_f32_e32 v242, v242, v243
	v_add_f32_e32 v244, v244, v245
	v_add_f32_e32 v248, v248, v249
	v_add_f32_e32 v250, v250, v251
	v_add_f32_e32 v252, v252, v253
	v_add_f32_e32 v254, v254, v255
	v_add_f32_e32 v176, v222, v224
	v_add_f32_e32 v177, v226, v228
	v_add_f32_e32 v178, v230, v232
	v_add_f32_e32 v179, v234, v236
	v_add_f32_e32 v180, v238, v240
	v_add_f32_e32 v181, v242, v244
	v_add_f32_e32 v182, v248, v250
	v_add_f32_e32 v183, v252, v254
	v_mov_b32_e32 v184, v176
	v_mov_b32_e32 v185, v177
	v_mov_b32_e32 v186, v178
	v_mov_b32_e32 v187, v179
	v_mov_b32_e32 v188, v180
	v_mov_b32_e32 v189, v181
	v_mov_b32_e32 v190, v182
	v_mov_b32_e32 v191, v183
	v_permlane16_swap_b32_e32 v176, v184
	v_permlane16_swap_b32_e32 v177, v185
	v_permlane16_swap_b32_e32 v178, v186
	v_permlane16_swap_b32_e32 v179, v187
	v_permlane16_swap_b32_e32 v180, v188
	v_permlane16_swap_b32_e32 v181, v189
	v_permlane16_swap_b32_e32 v182, v190
	v_permlane16_swap_b32_e32 v183, v191
	v_add_f32_e32 v176, v176, v184
	v_add_f32_e32 v177, v177, v185
	v_add_f32_e32 v178, v178, v186
	v_add_f32_e32 v179, v179, v187
	v_add_f32_e32 v180, v180, v188
	v_add_f32_e32 v181, v181, v189
	v_add_f32_e32 v182, v182, v190
	v_add_f32_e32 v183, v183, v191
	v_mov_b32_e32 v184, v176
	v_mov_b32_e32 v185, v177
	v_mov_b32_e32 v186, v178
	v_mov_b32_e32 v187, v179
	v_mov_b32_e32 v188, v180
	v_mov_b32_e32 v189, v181
	v_mov_b32_e32 v190, v182
	v_mov_b32_e32 v191, v183
	v_permlane32_swap_b32_e32 v176, v184
	v_permlane32_swap_b32_e32 v177, v185
	v_permlane32_swap_b32_e32 v178, v186
	v_permlane32_swap_b32_e32 v179, v187
	v_permlane32_swap_b32_e32 v180, v188
	v_permlane32_swap_b32_e32 v181, v189
	v_permlane32_swap_b32_e32 v182, v190
	v_permlane32_swap_b32_e32 v183, v191
	v_add_f32_e32 v176, v176, v184
	v_add_f32_e32 v177, v177, v185
	v_add_f32_e32 v178, v178, v186
	v_add_f32_e32 v179, v179, v187
	v_add_f32_e32 v180, v180, v188
	v_add_f32_e32 v181, v181, v189
	v_add_f32_e32 v182, v182, v190
	v_add_f32_e32 v183, v183, v191
	v_fmamk_f32 v176, v176, 0x3a800000, v153
	v_fmamk_f32 v177, v177, 0x3a800000, v153
	v_fmamk_f32 v178, v178, 0x3a800000, v153
	v_fmamk_f32 v179, v179, 0x3a800000, v153
	v_fmamk_f32 v180, v180, 0x3a800000, v153
	v_fmamk_f32 v181, v181, 0x3a800000, v153
	v_fmamk_f32 v182, v182, 0x3a800000, v153
	v_fmamk_f32 v183, v183, 0x3a800000, v153
	v_rsq_f32_e32 v176, v176
	v_rsq_f32_e32 v177, v177
	v_rsq_f32_e32 v178, v178
	v_rsq_f32_e32 v179, v179
	v_rsq_f32_e32 v180, v180
	v_rsq_f32_e32 v181, v181
	v_rsq_f32_e32 v182, v182
	v_rsq_f32_e32 v183, v183
	v_lshl_add_u32 v192, s22, 14, v246
	v_add_u32_e32 v193, 0x2000, v192
	global_load_dwordx4 v[222:225], v192, s[90:91]
	global_load_dwordx4 v[226:229], v192, s[90:91] offset:1024
	global_load_dwordx4 v[230:233], v192, s[90:91] offset:2048
	global_load_dwordx4 v[234:237], v192, s[90:91] offset:3072
	global_load_dwordx4 v[238:241], v193, s[90:91]
	global_load_dwordx4 v[242:245], v193, s[90:91] offset:1024
	global_load_dwordx4 v[248:251], v193, s[90:91] offset:2048
	global_load_dwordx4 v[252:255], v193, s[90:91] offset:3072
	v_lshl_add_u32 v148, s30, 8, v1
	v_ashrrev_i32_e32 v149, 31, v148
	v_lshlrev_b64 v[142:143], 6, v[148:149]
	v_lshl_add_u64 v[142:143], s[90:91], 0, v[142:143]
	v_lshl_or_b32 v144, s28, 7, v151
	v_mov_b64_e32 v[142:143], s[14:15]
	v_ashrrev_i32_e32 v145, 31, v144
	v_mad_i64_i32 v[170:171], s[4:5], v148, s58, v[142:143]
	v_lshlrev_b64 v[144:145], 1, v[144:145]
	v_or_b32_e32 v172, 16, v148
	v_ashrrev_i32_e32 v173, 31, v172
	s_nop 0
	v_lshlrev_b64 v[156:157], 6, v[172:173]
	v_lshl_add_u64 v[156:157], s[90:91], 0, v[156:157]
	s_nop 0
	v_lshl_add_u64 v[154:155], v[170:171], 0, v[144:145]
	v_mov_b32_e32 v158, v176
	v_pk_mul_f32 v[126:127], v[126:127], v[158:159] op_sel_hi:[1,0]
	v_pk_mul_f32 v[128:129], v[128:129], v[158:159] op_sel_hi:[1,0]
	v_pk_mul_f32 v[122:123], v[122:123], v[158:159] op_sel_hi:[1,0]
	v_pk_mul_f32 v[124:125], v[124:125], v[158:159] op_sel_hi:[1,0]
	v_pk_mul_f32 v[118:119], v[118:119], v[158:159] op_sel_hi:[1,0]
	v_pk_mul_f32 v[120:121], v[120:121], v[158:159] op_sel_hi:[1,0]
	v_pk_mul_f32 v[114:115], v[114:115], v[158:159] op_sel_hi:[1,0]
	v_pk_mul_f32 v[116:117], v[116:117], v[158:159] op_sel_hi:[1,0]
	v_mul_f32_e32 v149, 0xbfb8aa3b, v126
	v_mul_f32_e32 v158, 0xbfb8aa3b, v127
	v_mul_f32_e32 v159, 0xbfb8aa3b, v128
	v_mul_f32_e32 v160, 0xbfb8aa3b, v129
	v_mul_f32_e32 v161, 0xbfb8aa3b, v122
	v_mul_f32_e32 v162, 0xbfb8aa3b, v123
	v_mul_f32_e32 v163, 0xbfb8aa3b, v124
	v_mul_f32_e32 v164, 0xbfb8aa3b, v125
	v_exp_f32_e32 v149, v149
	v_exp_f32_e32 v158, v158
	v_exp_f32_e32 v159, v159
	v_exp_f32_e32 v160, v160
	v_exp_f32_e32 v161, v161
	v_exp_f32_e32 v162, v162
	v_exp_f32_e32 v163, v163
	v_exp_f32_e32 v164, v164
	v_add_f32_e32 v149, 1.0, v149
	v_add_f32_e32 v165, 1.0, v158
	v_add_f32_e32 v166, 1.0, v159
	v_add_f32_e32 v167, 1.0, v160
	v_add_f32_e32 v168, 1.0, v161
	v_add_f32_e32 v169, 1.0, v162
	v_add_f32_e32 v170, 1.0, v163
	v_add_f32_e32 v171, 1.0, v164
	v_rcp_f32_e32 v158, v149
	v_rcp_f32_e32 v159, v165
	v_rcp_f32_e32 v160, v166
	v_rcp_f32_e32 v161, v167
	v_rcp_f32_e32 v162, v168
	v_rcp_f32_e32 v163, v169
	v_rcp_f32_e32 v164, v170
	v_rcp_f32_e32 v165, v171
	v_pk_mul_f32 v[126:127], v[126:127], v[158:159]
	v_pk_mul_f32 v[128:129], v[128:129], v[160:161]
	v_pk_mul_f32 v[122:123], v[122:123], v[162:163]
; __device__ __forceinline__ float silu_f(float x) { return x * __builtin_amdgcn_rcpf(1.0f + __expf(-x)); }
; __device__ __forceinline__ u32x4 pack8(const f32x4 a, const f32x4 b) { u32x4 w; w.x = cvt_pk_bf16(a[0], a[1]); w.y = cvt_pk_bf16(a[2], a[3]); w.z = cvt_pk_bf16(b[0], b[1]); w.w = cvt_pk_bf16(b[2], b[3]); return w; }
;     __device__ __forceinline__ void operator()(const Acc& acc, const pg8::Unit& u, int wr, int wc, int fr, int fq) const {
;     ...
;         for (int ai = 0; ai < 2; ++ai)
; #pragma unroll
;             for (int m = 0; m < 4; ++m) {
;                 const int row = u.pm * 256 + ai * 128 + wr * 64 + m * 16 + fr;
;                 const float rs = row_rs(part, row);
;                 const int col = u.pn * 128 + wc * 32 + 8 * fq;
;                 f32x4 h[2];
; #pragma unroll
;                 for (int n = 0; n < 2; ++n)
; #pragma unroll
;                     for (int e = 0; e < 4; ++e) h[n][e] = silu_f(acc[ai][0][m][n][e] * rs) * (acc[ai][1][m][n][e] * rs);
;                 *(u32x4*)(hff + (size_t)row * DFF + col) = pack8(h[0], h[1]);
	v_pk_mul_f32 v[124:125], v[124:125], v[164:165]
	v_pk_mul_f32 v[118:119], v[118:119], v[126:127]
	v_pk_mul_f32 v[120:121], v[120:121], v[128:129]
	v_pk_mul_f32 v[122:123], v[114:115], v[122:123]
	v_pk_mul_f32 v[124:125], v[116:117], v[124:125]
	v_cvt_pk_bf16_f32 v114, v118, v119
	v_cvt_pk_bf16_f32 v115, v120, v121
	v_cvt_pk_bf16_f32 v116, v122, v123
	v_cvt_pk_bf16_f32 v117, v124, v125
	global_store_dwordx4 v[154:155], v[114:117], off
	s_nop 0
	v_or_b32_e32 v154, 32, v148
	v_mad_i64_i32 v[156:157], s[4:5], v172, s58, v[142:143]
	v_ashrrev_i32_e32 v155, 31, v154
	s_nop 0
	v_lshlrev_b64 v[116:117], 6, v[154:155]
	v_lshl_add_u64 v[116:117], s[90:91], 0, v[116:117]
	s_nop 0
	v_lshl_add_u64 v[114:115], v[156:157], 0, v[144:145]
	v_mov_b32_e32 v118, v177
	v_pk_mul_f32 v[110:111], v[110:111], v[118:119] op_sel_hi:[1,0]
	v_pk_mul_f32 v[112:113], v[112:113], v[118:119] op_sel_hi:[1,0]
	v_pk_mul_f32 v[106:107], v[106:107], v[118:119] op_sel_hi:[1,0]
	v_pk_mul_f32 v[108:109], v[108:109], v[118:119] op_sel_hi:[1,0]
	v_pk_mul_f32 v[102:103], v[102:103], v[118:119] op_sel_hi:[1,0]
	v_pk_mul_f32 v[104:105], v[104:105], v[118:119] op_sel_hi:[1,0]
	v_pk_mul_f32 v[98:99], v[98:99], v[118:119] op_sel_hi:[1,0]
	v_pk_mul_f32 v[100:101], v[100:101], v[118:119] op_sel_hi:[1,0]
	v_mul_f32_e32 v118, 0xbfb8aa3b, v110
	v_mul_f32_e32 v119, 0xbfb8aa3b, v111
	v_mul_f32_e32 v120, 0xbfb8aa3b, v112
	v_mul_f32_e32 v121, 0xbfb8aa3b, v113
	v_mul_f32_e32 v122, 0xbfb8aa3b, v106
	v_mul_f32_e32 v123, 0xbfb8aa3b, v107
	v_mul_f32_e32 v124, 0xbfb8aa3b, v108
	v_mul_f32_e32 v125, 0xbfb8aa3b, v109
	v_exp_f32_e32 v118, v118
	v_exp_f32_e32 v119, v119
	v_exp_f32_e32 v120, v120
	v_exp_f32_e32 v121, v121
	v_exp_f32_e32 v122, v122
	v_exp_f32_e32 v123, v123
	v_exp_f32_e32 v124, v124
	v_exp_f32_e32 v125, v125
	v_add_f32_e32 v118, 1.0, v118
	v_add_f32_e32 v119, 1.0, v119
	v_add_f32_e32 v120, 1.0, v120
	v_add_f32_e32 v121, 1.0, v121
	v_add_f32_e32 v122, 1.0, v122
	v_add_f32_e32 v123, 1.0, v123
	v_add_f32_e32 v124, 1.0, v124
	v_add_f32_e32 v125, 1.0, v125
	v_rcp_f32_e32 v118, v118
	v_rcp_f32_e32 v119, v119
	v_rcp_f32_e32 v120, v120
	v_rcp_f32_e32 v121, v121
	v_rcp_f32_e32 v122, v122
	v_rcp_f32_e32 v123, v123
	v_rcp_f32_e32 v124, v124
	v_rcp_f32_e32 v125, v125
	v_pk_mul_f32 v[110:111], v[110:111], v[118:119]
	v_pk_mul_f32 v[112:113], v[112:113], v[120:121]
	v_pk_mul_f32 v[106:107], v[106:107], v[122:123]
	v_pk_mul_f32 v[108:109], v[108:109], v[124:125]
	v_pk_mul_f32 v[102:103], v[102:103], v[110:111]
	v_pk_mul_f32 v[104:105], v[104:105], v[112:113]
	v_pk_mul_f32 v[106:107], v[98:99], v[106:107]
	v_pk_mul_f32 v[108:109], v[100:101], v[108:109]
	v_cvt_pk_bf16_f32 v98, v102, v103
	v_cvt_pk_bf16_f32 v99, v104, v105
	v_cvt_pk_bf16_f32 v100, v106, v107
	v_cvt_pk_bf16_f32 v101, v108, v109
	global_store_dwordx4 v[114:115], v[98:101], off
	s_nop 0
	v_or_b32_e32 v114, 48, v148
	v_mad_i64_i32 v[116:117], s[4:5], v154, s58, v[142:143]
	v_ashrrev_i32_e32 v115, 31, v114
	s_nop 0
	v_lshlrev_b64 v[100:101], 6, v[114:115]
	v_lshl_add_u64 v[100:101], s[90:91], 0, v[100:101]
	s_nop 0
	v_lshl_add_u64 v[98:99], v[116:117], 0, v[144:145]
	v_mov_b32_e32 v102, v178
	v_pk_mul_f32 v[94:95], v[94:95], v[102:103] op_sel_hi:[1,0]
	v_pk_mul_f32 v[96:97], v[96:97], v[102:103] op_sel_hi:[1,0]
	v_pk_mul_f32 v[90:91], v[90:91], v[102:103] op_sel_hi:[1,0]
	v_pk_mul_f32 v[92:93], v[92:93], v[102:103] op_sel_hi:[1,0]
	v_pk_mul_f32 v[86:87], v[86:87], v[102:103] op_sel_hi:[1,0]
	v_pk_mul_f32 v[88:89], v[88:89], v[102:103] op_sel_hi:[1,0]
	v_pk_mul_f32 v[82:83], v[82:83], v[102:103] op_sel_hi:[1,0]
	v_pk_mul_f32 v[84:85], v[84:85], v[102:103] op_sel_hi:[1,0]
	v_mul_f32_e32 v102, 0xbfb8aa3b, v94
	v_mul_f32_e32 v103, 0xbfb8aa3b, v95
	v_mul_f32_e32 v104, 0xbfb8aa3b, v96
	v_mul_f32_e32 v105, 0xbfb8aa3b, v97
	v_mul_f32_e32 v106, 0xbfb8aa3b, v90
	v_mul_f32_e32 v107, 0xbfb8aa3b, v91
	v_mul_f32_e32 v108, 0xbfb8aa3b, v92
	v_mul_f32_e32 v109, 0xbfb8aa3b, v93
	v_exp_f32_e32 v102, v102
	v_exp_f32_e32 v103, v103
	v_exp_f32_e32 v104, v104
	v_exp_f32_e32 v105, v105
	v_exp_f32_e32 v106, v106
	v_exp_f32_e32 v107, v107
	v_exp_f32_e32 v108, v108
	v_exp_f32_e32 v109, v109
	v_add_f32_e32 v102, 1.0, v102
	v_add_f32_e32 v103, 1.0, v103
	v_add_f32_e32 v104, 1.0, v104
	v_add_f32_e32 v105, 1.0, v105
	v_add_f32_e32 v106, 1.0, v106
	v_add_f32_e32 v107, 1.0, v107
	v_add_f32_e32 v108, 1.0, v108
	v_add_f32_e32 v109, 1.0, v109
	v_rcp_f32_e32 v102, v102
	v_rcp_f32_e32 v103, v103
	v_rcp_f32_e32 v104, v104
	v_rcp_f32_e32 v105, v105
	v_rcp_f32_e32 v106, v106
	v_rcp_f32_e32 v107, v107
	v_rcp_f32_e32 v108, v108
	v_rcp_f32_e32 v109, v109
	v_pk_mul_f32 v[94:95], v[94:95], v[102:103]
	v_pk_mul_f32 v[96:97], v[96:97], v[104:105]
	v_pk_mul_f32 v[90:91], v[90:91], v[106:107]
	v_pk_mul_f32 v[92:93], v[92:93], v[108:109]
	v_pk_mul_f32 v[86:87], v[86:87], v[94:95]
	v_pk_mul_f32 v[88:89], v[88:89], v[96:97]
	v_pk_mul_f32 v[90:91], v[82:83], v[90:91]
	v_pk_mul_f32 v[92:93], v[84:85], v[92:93]
	v_cvt_pk_bf16_f32 v82, v86, v87
	v_cvt_pk_bf16_f32 v83, v88, v89
	v_cvt_pk_bf16_f32 v84, v90, v91
	v_cvt_pk_bf16_f32 v85, v92, v93
	global_store_dwordx4 v[98:99], v[82:85], off
	s_nop 0
	v_add_u32_e32 v98, 0x80, v148
	v_mad_i64_i32 v[100:101], s[4:5], v114, s58, v[142:143]
	v_ashrrev_i32_e32 v99, 31, v98
	s_nop 0
	v_lshlrev_b64 v[84:85], 6, v[98:99]
	v_lshl_add_u64 v[84:85], s[90:91], 0, v[84:85]
	s_nop 0
	v_lshl_add_u64 v[82:83], v[100:101], 0, v[144:145]
	v_mov_b32_e32 v86, v179
	v_pk_mul_f32 v[78:79], v[78:79], v[86:87] op_sel_hi:[1,0]
	v_pk_mul_f32 v[80:81], v[80:81], v[86:87] op_sel_hi:[1,0]
	v_pk_mul_f32 v[74:75], v[74:75], v[86:87] op_sel_hi:[1,0]
	v_pk_mul_f32 v[76:77], v[76:77], v[86:87] op_sel_hi:[1,0]
; __device__ __forceinline__ float silu_f(float x) { return x * __builtin_amdgcn_rcpf(1.0f + __expf(-x)); }
; __device__ __forceinline__ u32x4 pack8(const f32x4 a, const f32x4 b) { u32x4 w; w.x = cvt_pk_bf16(a[0], a[1]); w.y = cvt_pk_bf16(a[2], a[3]); w.z = cvt_pk_bf16(b[0], b[1]); w.w = cvt_pk_bf16(b[2], b[3]); return w; }
;     __device__ __forceinline__ void operator()(const Acc& acc, const pg8::Unit& u, int wr, int wc, int fr, int fq) const {
;     ...
;         for (int ai = 0; ai < 2; ++ai)
; #pragma unroll
;             for (int m = 0; m < 4; ++m) {
;                 const int row = u.pm * 256 + ai * 128 + wr * 64 + m * 16 + fr;
;                 const float rs = row_rs(part, row);
;                 const int col = u.pn * 128 + wc * 32 + 8 * fq;
;                 f32x4 h[2];
; #pragma unroll
;                 for (int n = 0; n < 2; ++n)
; #pragma unroll
;                     for (int e = 0; e < 4; ++e) h[n][e] = silu_f(acc[ai][0][m][n][e] * rs) * (acc[ai][1][m][n][e] * rs);
;                 *(u32x4*)(hff + (size_t)row * DFF + col) = pack8(h[0], h[1]);
	v_pk_mul_f32 v[70:71], v[70:71], v[86:87] op_sel_hi:[1,0]
	v_pk_mul_f32 v[72:73], v[72:73], v[86:87] op_sel_hi:[1,0]
	v_pk_mul_f32 v[66:67], v[66:67], v[86:87] op_sel_hi:[1,0]
	v_pk_mul_f32 v[68:69], v[68:69], v[86:87] op_sel_hi:[1,0]
	v_mul_f32_e32 v86, 0xbfb8aa3b, v78
	v_mul_f32_e32 v87, 0xbfb8aa3b, v79
	v_mul_f32_e32 v88, 0xbfb8aa3b, v80
	v_mul_f32_e32 v89, 0xbfb8aa3b, v81
	v_mul_f32_e32 v90, 0xbfb8aa3b, v74
	v_mul_f32_e32 v91, 0xbfb8aa3b, v75
	v_mul_f32_e32 v92, 0xbfb8aa3b, v76
	v_mul_f32_e32 v93, 0xbfb8aa3b, v77
	v_exp_f32_e32 v86, v86
	v_exp_f32_e32 v87, v87
	v_exp_f32_e32 v88, v88
	v_exp_f32_e32 v89, v89
	v_exp_f32_e32 v90, v90
	v_exp_f32_e32 v91, v91
	v_exp_f32_e32 v92, v92
	v_exp_f32_e32 v93, v93
	v_add_f32_e32 v86, 1.0, v86
	v_add_f32_e32 v87, 1.0, v87
	v_add_f32_e32 v88, 1.0, v88
	v_add_f32_e32 v89, 1.0, v89
	v_add_f32_e32 v90, 1.0, v90
	v_add_f32_e32 v91, 1.0, v91
	v_add_f32_e32 v92, 1.0, v92
	v_add_f32_e32 v93, 1.0, v93
	v_rcp_f32_e32 v86, v86
	v_rcp_f32_e32 v87, v87
	v_rcp_f32_e32 v88, v88
	v_rcp_f32_e32 v89, v89
	v_rcp_f32_e32 v90, v90
	v_rcp_f32_e32 v91, v91
	v_rcp_f32_e32 v92, v92
	v_rcp_f32_e32 v93, v93
	v_pk_mul_f32 v[78:79], v[78:79], v[86:87]
	v_pk_mul_f32 v[80:81], v[80:81], v[88:89]
	v_pk_mul_f32 v[74:75], v[74:75], v[90:91]
	v_pk_mul_f32 v[76:77], v[76:77], v[92:93]
	v_pk_mul_f32 v[70:71], v[70:71], v[78:79]
	v_pk_mul_f32 v[72:73], v[72:73], v[80:81]
	v_pk_mul_f32 v[74:75], v[66:67], v[74:75]
	v_pk_mul_f32 v[76:77], v[68:69], v[76:77]
	v_cvt_pk_bf16_f32 v66, v70, v71
	v_cvt_pk_bf16_f32 v67, v72, v73
	v_cvt_pk_bf16_f32 v68, v74, v75
	v_cvt_pk_bf16_f32 v69, v76, v77
	global_store_dwordx4 v[82:83], v[66:69], off
	s_nop 0
	v_add_u32_e32 v82, 0x90, v148
	v_mad_i64_i32 v[84:85], s[4:5], v98, s58, v[142:143]
	v_ashrrev_i32_e32 v83, 31, v82
	s_nop 0
	v_lshlrev_b64 v[68:69], 6, v[82:83]
	v_lshl_add_u64 v[68:69], s[90:91], 0, v[68:69]
	s_nop 0
	v_lshl_add_u64 v[66:67], v[84:85], 0, v[144:145]
	v_mov_b32_e32 v70, v180
	v_pk_mul_f32 v[62:63], v[62:63], v[70:71] op_sel_hi:[1,0]
	v_pk_mul_f32 v[64:65], v[64:65], v[70:71] op_sel_hi:[1,0]
	v_pk_mul_f32 v[58:59], v[58:59], v[70:71] op_sel_hi:[1,0]
	v_pk_mul_f32 v[60:61], v[60:61], v[70:71] op_sel_hi:[1,0]
	v_pk_mul_f32 v[54:55], v[54:55], v[70:71] op_sel_hi:[1,0]
	v_pk_mul_f32 v[56:57], v[56:57], v[70:71] op_sel_hi:[1,0]
	v_pk_mul_f32 v[50:51], v[50:51], v[70:71] op_sel_hi:[1,0]
	v_pk_mul_f32 v[52:53], v[52:53], v[70:71] op_sel_hi:[1,0]
	v_mul_f32_e32 v70, 0xbfb8aa3b, v62
	v_mul_f32_e32 v71, 0xbfb8aa3b, v63
	v_mul_f32_e32 v72, 0xbfb8aa3b, v64
	v_mul_f32_e32 v73, 0xbfb8aa3b, v65
	v_mul_f32_e32 v74, 0xbfb8aa3b, v58
	v_mul_f32_e32 v75, 0xbfb8aa3b, v59
	v_mul_f32_e32 v76, 0xbfb8aa3b, v60
	v_mul_f32_e32 v77, 0xbfb8aa3b, v61
	v_exp_f32_e32 v70, v70
	v_exp_f32_e32 v71, v71
	v_exp_f32_e32 v72, v72
	v_exp_f32_e32 v73, v73
	v_exp_f32_e32 v74, v74
	v_exp_f32_e32 v75, v75
	v_exp_f32_e32 v76, v76
	v_exp_f32_e32 v77, v77
	v_add_f32_e32 v70, 1.0, v70
	v_add_f32_e32 v71, 1.0, v71
	v_add_f32_e32 v72, 1.0, v72
	v_add_f32_e32 v73, 1.0, v73
	v_add_f32_e32 v74, 1.0, v74
	v_add_f32_e32 v75, 1.0, v75
	v_add_f32_e32 v76, 1.0, v76
	v_add_f32_e32 v77, 1.0, v77
	v_rcp_f32_e32 v70, v70
	v_rcp_f32_e32 v71, v71
	v_rcp_f32_e32 v72, v72
	v_rcp_f32_e32 v73, v73
	v_rcp_f32_e32 v74, v74
	v_rcp_f32_e32 v75, v75
	v_rcp_f32_e32 v76, v76
	v_rcp_f32_e32 v77, v77
	v_pk_mul_f32 v[62:63], v[62:63], v[70:71]
	v_pk_mul_f32 v[64:65], v[64:65], v[72:73]
	v_pk_mul_f32 v[58:59], v[58:59], v[74:75]
	v_pk_mul_f32 v[60:61], v[60:61], v[76:77]
	v_pk_mul_f32 v[54:55], v[54:55], v[62:63]
	v_pk_mul_f32 v[56:57], v[56:57], v[64:65]
	v_pk_mul_f32 v[58:59], v[50:51], v[58:59]
	v_pk_mul_f32 v[60:61], v[52:53], v[60:61]
	v_cvt_pk_bf16_f32 v50, v54, v55
	v_cvt_pk_bf16_f32 v51, v56, v57
	v_cvt_pk_bf16_f32 v52, v58, v59
	v_cvt_pk_bf16_f32 v53, v60, v61
	global_store_dwordx4 v[66:67], v[50:53], off
	s_nop 0
	v_add_u32_e32 v66, 0xa0, v148
	v_mad_i64_i32 v[68:69], s[4:5], v82, s58, v[142:143]
	v_ashrrev_i32_e32 v67, 31, v66
	s_nop 0
	v_lshlrev_b64 v[52:53], 6, v[66:67]
	v_lshl_add_u64 v[52:53], s[90:91], 0, v[52:53]
	s_nop 0
	v_lshl_add_u64 v[50:51], v[68:69], 0, v[144:145]
	v_mov_b32_e32 v54, v181
	v_pk_mul_f32 v[46:47], v[46:47], v[54:55] op_sel_hi:[1,0]
	v_pk_mul_f32 v[48:49], v[48:49], v[54:55] op_sel_hi:[1,0]
	v_pk_mul_f32 v[42:43], v[42:43], v[54:55] op_sel_hi:[1,0]
	v_pk_mul_f32 v[44:45], v[44:45], v[54:55] op_sel_hi:[1,0]
	v_pk_mul_f32 v[38:39], v[38:39], v[54:55] op_sel_hi:[1,0]
	v_pk_mul_f32 v[40:41], v[40:41], v[54:55] op_sel_hi:[1,0]
	v_pk_mul_f32 v[34:35], v[34:35], v[54:55] op_sel_hi:[1,0]
	v_pk_mul_f32 v[36:37], v[36:37], v[54:55] op_sel_hi:[1,0]
	v_mul_f32_e32 v54, 0xbfb8aa3b, v46
	v_mul_f32_e32 v55, 0xbfb8aa3b, v47
	v_mul_f32_e32 v56, 0xbfb8aa3b, v48
	v_mul_f32_e32 v57, 0xbfb8aa3b, v49
	v_mul_f32_e32 v58, 0xbfb8aa3b, v42
	v_mul_f32_e32 v59, 0xbfb8aa3b, v43
	v_mul_f32_e32 v60, 0xbfb8aa3b, v44
	v_mul_f32_e32 v61, 0xbfb8aa3b, v45
	v_exp_f32_e32 v54, v54
	v_exp_f32_e32 v55, v55
	v_exp_f32_e32 v56, v56
	v_exp_f32_e32 v57, v57
	v_exp_f32_e32 v58, v58
	v_exp_f32_e32 v59, v59
	v_exp_f32_e32 v60, v60
	v_exp_f32_e32 v61, v61
	v_add_f32_e32 v54, 1.0, v54
	v_add_f32_e32 v55, 1.0, v55
	v_add_f32_e32 v56, 1.0, v56
	v_add_f32_e32 v57, 1.0, v57
; __device__ __forceinline__ float silu_f(float x) { return x * __builtin_amdgcn_rcpf(1.0f + __expf(-x)); }
; __device__ __forceinline__ u32x4 pack8(const f32x4 a, const f32x4 b) { u32x4 w; w.x = cvt_pk_bf16(a[0], a[1]); w.y = cvt_pk_bf16(a[2], a[3]); w.z = cvt_pk_bf16(b[0], b[1]); w.w = cvt_pk_bf16(b[2], b[3]); return w; }
; template <class Epi, class Sched, bool ALIGN_EPI = false, bool SP2 = false>
; __device__ __forceinline__ void gemm_phase(PG8_LAS unsigned char* lds, const Gemm g, const Sched& S, const Epi& E) {
;     ...
;     for (;;) {
;         const bool has_next = S.next(ui + 1, nxt);
;         const char* nA = has_next ? (const char*)g.A + (size_t)nxt.pm * tstep + (size_t)nxt.kt0 * kstep : cA; const char* nB = has_next ? (const char*)g.Bt + (size_t)nxt.pn * tstep + (size_t)nxt.kt0 * kstep : cB;
;         const int nt = cur.nt;
;         for (int t = 0; t < nt; t += 2) {
;     __device__ __forceinline__ void operator()(const Acc& acc, const pg8::Unit& u, int wr, int wc, int fr, int fq) const {
;     ...
;         for (int ai = 0; ai < 2; ++ai)
; #pragma unroll
;             for (int m = 0; m < 4; ++m) {
;                 const int row = u.pm * 256 + ai * 128 + wr * 64 + m * 16 + fr;
;                 const float rs = row_rs(part, row);
;                 const int col = u.pn * 128 + wc * 32 + 8 * fq;
;                 f32x4 h[2];
; #pragma unroll
;                 for (int n = 0; n < 2; ++n)
; #pragma unroll
;                     for (int e = 0; e < 4; ++e) h[n][e] = silu_f(acc[ai][0][m][n][e] * rs) * (acc[ai][1][m][n][e] * rs);
;                 *(u32x4*)(hff + (size_t)row * DFF + col) = pack8(h[0], h[1]);
	v_add_f32_e32 v58, 1.0, v58
	v_add_f32_e32 v59, 1.0, v59
	v_add_f32_e32 v60, 1.0, v60
	v_add_f32_e32 v61, 1.0, v61
	v_rcp_f32_e32 v54, v54
	v_rcp_f32_e32 v55, v55
	v_rcp_f32_e32 v56, v56
	v_rcp_f32_e32 v57, v57
	v_rcp_f32_e32 v58, v58
	v_rcp_f32_e32 v59, v59
	v_rcp_f32_e32 v60, v60
	v_rcp_f32_e32 v61, v61
	v_pk_mul_f32 v[46:47], v[46:47], v[54:55]
	v_pk_mul_f32 v[48:49], v[48:49], v[56:57]
	v_pk_mul_f32 v[42:43], v[42:43], v[58:59]
	v_pk_mul_f32 v[44:45], v[44:45], v[60:61]
	v_pk_mul_f32 v[38:39], v[38:39], v[46:47]
	v_pk_mul_f32 v[40:41], v[40:41], v[48:49]
	v_pk_mul_f32 v[42:43], v[34:35], v[42:43]
	v_pk_mul_f32 v[44:45], v[36:37], v[44:45]
	v_cvt_pk_bf16_f32 v34, v38, v39
	v_cvt_pk_bf16_f32 v35, v40, v41
	v_cvt_pk_bf16_f32 v36, v42, v43
	v_cvt_pk_bf16_f32 v37, v44, v45
	global_store_dwordx4 v[50:51], v[34:37], off
	s_nop 0
	v_add_u32_e32 v50, 0xb0, v148
	v_mad_i64_i32 v[52:53], s[4:5], v66, s58, v[142:143]
	v_ashrrev_i32_e32 v51, 31, v50
	s_nop 0
	v_lshlrev_b64 v[36:37], 6, v[50:51]
	v_lshl_add_u64 v[36:37], s[90:91], 0, v[36:37]
	s_nop 0
	v_lshl_add_u64 v[34:35], v[52:53], 0, v[144:145]
	v_mov_b32_e32 v38, v182
	v_pk_mul_f32 v[30:31], v[30:31], v[38:39] op_sel_hi:[1,0]
	v_pk_mul_f32 v[32:33], v[32:33], v[38:39] op_sel_hi:[1,0]
	v_pk_mul_f32 v[26:27], v[26:27], v[38:39] op_sel_hi:[1,0]
	v_pk_mul_f32 v[28:29], v[28:29], v[38:39] op_sel_hi:[1,0]
	v_pk_mul_f32 v[22:23], v[22:23], v[38:39] op_sel_hi:[1,0]
	v_pk_mul_f32 v[24:25], v[24:25], v[38:39] op_sel_hi:[1,0]
	v_pk_mul_f32 v[18:19], v[18:19], v[38:39] op_sel_hi:[1,0]
	v_pk_mul_f32 v[20:21], v[20:21], v[38:39] op_sel_hi:[1,0]
	v_mul_f32_e32 v38, 0xbfb8aa3b, v30
	v_mul_f32_e32 v39, 0xbfb8aa3b, v31
	v_mul_f32_e32 v40, 0xbfb8aa3b, v32
	v_mul_f32_e32 v41, 0xbfb8aa3b, v33
	v_mul_f32_e32 v42, 0xbfb8aa3b, v26
	v_mul_f32_e32 v43, 0xbfb8aa3b, v27
	v_mul_f32_e32 v44, 0xbfb8aa3b, v28
	v_mul_f32_e32 v45, 0xbfb8aa3b, v29
	v_exp_f32_e32 v38, v38
	v_exp_f32_e32 v39, v39
	v_exp_f32_e32 v40, v40
	v_exp_f32_e32 v41, v41
	v_exp_f32_e32 v42, v42
	v_exp_f32_e32 v43, v43
	v_exp_f32_e32 v44, v44
	v_exp_f32_e32 v45, v45
	v_add_f32_e32 v38, 1.0, v38
	v_add_f32_e32 v39, 1.0, v39
	v_add_f32_e32 v40, 1.0, v40
	v_add_f32_e32 v41, 1.0, v41
	v_add_f32_e32 v42, 1.0, v42
	v_add_f32_e32 v43, 1.0, v43
	v_add_f32_e32 v44, 1.0, v44
	v_add_f32_e32 v45, 1.0, v45
	v_rcp_f32_e32 v38, v38
	v_rcp_f32_e32 v39, v39
	v_rcp_f32_e32 v40, v40
	v_rcp_f32_e32 v41, v41
	v_rcp_f32_e32 v42, v42
	v_rcp_f32_e32 v43, v43
	v_rcp_f32_e32 v44, v44
	v_rcp_f32_e32 v45, v45
	v_pk_mul_f32 v[30:31], v[30:31], v[38:39]
	v_pk_mul_f32 v[32:33], v[32:33], v[40:41]
	v_pk_mul_f32 v[26:27], v[26:27], v[42:43]
	v_pk_mul_f32 v[28:29], v[28:29], v[44:45]
	v_pk_mul_f32 v[22:23], v[22:23], v[30:31]
	v_pk_mul_f32 v[24:25], v[24:25], v[32:33]
	v_pk_mul_f32 v[26:27], v[18:19], v[26:27]
	v_pk_mul_f32 v[28:29], v[20:21], v[28:29]
	v_cvt_pk_bf16_f32 v18, v22, v23
	v_cvt_pk_bf16_f32 v19, v24, v25
	v_cvt_pk_bf16_f32 v20, v26, v27
	v_cvt_pk_bf16_f32 v21, v28, v29
	global_store_dwordx4 v[34:35], v[18:21], off
	s_nop 0
	s_andn2_b64 vcc, exec, s[2:3]
	s_mov_b64 s[2:3], -1
	s_nop 0
	s_nop 0
	s_nop 1
	v_mad_i64_i32 v[18:19], s[34:35], v50, s58, v[142:143]
	v_lshl_add_u64 v[18:19], v[18:19], 0, v[144:145]
	v_mov_b32_e32 v20, v183
	v_pk_mul_f32 v[14:15], v[14:15], v[20:21] op_sel_hi:[1,0]
	v_pk_mul_f32 v[16:17], v[16:17], v[20:21] op_sel_hi:[1,0]
	v_pk_mul_f32 v[10:11], v[10:11], v[20:21] op_sel_hi:[1,0]
	v_pk_mul_f32 v[12:13], v[12:13], v[20:21] op_sel_hi:[1,0]
	v_pk_mul_f32 v[6:7], v[6:7], v[20:21] op_sel_hi:[1,0]
	v_pk_mul_f32 v[8:9], v[8:9], v[20:21] op_sel_hi:[1,0]
	v_pk_mul_f32 v[2:3], v[2:3], v[20:21] op_sel_hi:[1,0]
	v_pk_mul_f32 v[4:5], v[4:5], v[20:21] op_sel_hi:[1,0]
	v_mul_f32_e32 v20, 0xbfb8aa3b, v14
	v_mul_f32_e32 v21, 0xbfb8aa3b, v15
	v_mul_f32_e32 v22, 0xbfb8aa3b, v16
	v_mul_f32_e32 v23, 0xbfb8aa3b, v17
	v_mul_f32_e32 v24, 0xbfb8aa3b, v10
	v_mul_f32_e32 v25, 0xbfb8aa3b, v11
	v_mul_f32_e32 v26, 0xbfb8aa3b, v12
	v_mul_f32_e32 v27, 0xbfb8aa3b, v13
	v_exp_f32_e32 v20, v20
	v_exp_f32_e32 v21, v21
	v_exp_f32_e32 v22, v22
	v_exp_f32_e32 v23, v23
	v_exp_f32_e32 v24, v24
	v_exp_f32_e32 v25, v25
	v_exp_f32_e32 v26, v26
	v_exp_f32_e32 v27, v27
	v_add_f32_e32 v20, 1.0, v20
	v_add_f32_e32 v21, 1.0, v21
	v_add_f32_e32 v22, 1.0, v22
	v_add_f32_e32 v23, 1.0, v23
	v_add_f32_e32 v24, 1.0, v24
	v_add_f32_e32 v25, 1.0, v25
	v_add_f32_e32 v26, 1.0, v26
	v_add_f32_e32 v27, 1.0, v27
	v_rcp_f32_e32 v20, v20
	v_rcp_f32_e32 v21, v21
	v_rcp_f32_e32 v22, v22
	v_rcp_f32_e32 v23, v23
	v_rcp_f32_e32 v24, v24
	v_rcp_f32_e32 v25, v25
	v_rcp_f32_e32 v26, v26
	v_rcp_f32_e32 v27, v27
	v_pk_mul_f32 v[14:15], v[14:15], v[20:21]
	v_pk_mul_f32 v[16:17], v[16:17], v[22:23]
	v_pk_mul_f32 v[10:11], v[10:11], v[24:25]
	v_pk_mul_f32 v[12:13], v[12:13], v[26:27]
	v_pk_mul_f32 v[6:7], v[6:7], v[14:15]
	v_pk_mul_f32 v[8:9], v[8:9], v[16:17]
	v_pk_mul_f32 v[10:11], v[2:3], v[10:11]
	v_pk_mul_f32 v[12:13], v[4:5], v[12:13]
	v_cvt_pk_bf16_f32 v2, v6, v7
	v_cvt_pk_bf16_f32 v3, v8, v9
	v_cvt_pk_bf16_f32 v4, v10, v11
	v_cvt_pk_bf16_f32 v5, v12, v13
	global_store_dwordx4 v[18:19], v[2:5], off
	s_cbranch_vccnz .LBB0_573
	s_andn2_b64 vcc, exec, s[12:13]
	s_cbranch_vccnz .LBB0_572
	s_barrier
	s_branch .LBB0_572

; #define PG8_STAGE(bufoff, gbase, voff) do { _Pragma("unroll") for (int _i = 0; _i < 2; ++_i) \
;         __builtin_amdgcn_global_load_lds((const unsigned*)((const char*)(gbase) + (voff)[_i]), (PG8_LAS unsigned*)(lds + (bufoff) + ldsw + _i * 8192), 16, 0, 0); } while (0)
; #define PG8_WAIT_V(n) asm volatile("s_waitcnt vmcnt(" #n ")" ::: "memory")
; #define PG8_BAR __builtin_amdgcn_s_barrier()
; template <class Epi, class Sched, bool ALIGN_EPI = false, bool SP2 = false>
; __device__ __forceinline__ void gemm_phase(PG8_LAS unsigned char* lds, const Gemm g, const Sched& S, const Epi& E) {
;     ...
;     const char* cA = (const char*)g.A + (size_t)cur.pm * tstep + (size_t)cur.kt0 * kstep; const char* cB = (const char*)g.Bt + (size_t)cur.pn * tstep + (size_t)cur.kt0 * kstep;
;     S.a_ready(cur);
;     if constexpr (SP2) {
;         PG8_STAGE(PG8_SB(0, 0), cB, voffB); PG8_STAGE(PG8_SB(0, 1), cB + hstep, voffB); PG8_STAGE(PG8_SA(0, 0), cA, voffA); PG8_STAGE(PG8_SA(0, 1), cA + hstep, voffA);
;         if (wr == 1) PG8_BAR;
;         PG8_WAIT_V(2); PG8_BAR;
;         PG8_STAGE(PG8_SB(1, 0), cB + kstep, voffB); PG8_STAGE(PG8_SA(1, 0), cA + kstep, voffA); PG8_STAGE(PG8_SB(1, 1), cB + hstep + kstep, voffB);
;         PG8_WAIT_V(6); PG8_BAR;
; __device__ __forceinline__ float row_rs(const float* part, int row) {
;     const f32x4* p = (const f32x4*)(part + (size_t)row * 16);
;     const f32x4 a = p[0], b = p[1], c = p[2], d = p[3];
.LBB0_1343:
	v_and_b32_e32 v246, 15, v146
	v_lshrrev_b32_e32 v192, 8, v146
	v_lshl_or_b32 v246, v192, 6, v246
	v_bfe_u32 v192, v146, 4, 2
	v_lshlrev_b32_e32 v192, 4, v192
	v_lshl_or_b32 v246, v246, 6, v192
	v_lshl_add_u32 v192, s30, 14, v246
	v_add_u32_e32 v193, 0x2000, v192
	global_load_dwordx4 v[222:225], v192, s[90:91]
	global_load_dwordx4 v[226:229], v192, s[90:91] offset:1024
	global_load_dwordx4 v[230:233], v192, s[90:91] offset:2048
	global_load_dwordx4 v[234:237], v192, s[90:91] offset:3072
	global_load_dwordx4 v[238:241], v193, s[90:91]
	global_load_dwordx4 v[242:245], v193, s[90:91] offset:1024
	global_load_dwordx4 v[248:251], v193, s[90:91] offset:2048
	global_load_dwordx4 v[252:255], v193, s[90:91] offset:3072
	s_add_u32 s33, s74, 0x1300000
	s_addc_u32 s46, s75, 0
	s_ashr_i32 s31, s30, 31
	s_lshl_b64 s[0:1], s[30:31], 19
	s_add_u32 s34, s88, s0
	s_addc_u32 s35, s89, s1
	s_ashr_i32 s29, s28, 31
	s_lshl_b64 s[0:1], s[28:29], 19
	v_lshrrev_b32_e32 v5, 1, v146
	s_add_u32 s36, s33, s0
	v_and_b32_e32 v10, 24, v5
	v_and_b32_e32 v5, 4, v1
	v_bfe_u32 v6, v146, 2, 2
	s_addc_u32 s37, s46, s1
	v_lshlrev_b32_e32 v2, 4, v146
	v_and_b32_e32 v3, 32, v146
	v_bfe_u32 v4, v146, 2, 4
	v_or3_b32 v5, v5, v6, v10
	v_lshrrev_b32_e32 v6, 3, v146
	s_movk_i32 s1, 0x70
	v_bitop3_b32 v3, v2, v3, 48 bitop3:0x6c
	v_and_or_b32 v7, v6, s1, v4
	s_movk_i32 s1, 0x60
	v_add_u32_e32 v2, 0x2000, v2
	v_and_or_b32 v6, v6, s1, v5
	v_lshrrev_b32_e32 v2, 7, v2
	s_movk_i32 s1, 0xf0
	v_and_or_b32 v4, v2, s1, v4
	s_movk_i32 s1, 0xe0
	v_and_or_b32 v2, v2, s1, v5
	s_lshr_b32 s1, s4, 6
	s_lshl_b32 s29, s1, 10
	v_and_or_b32 v3, v146, 64, v3
	s_add_i32 s31, s29, 0
	v_lshl_or_b32 v132, v6, 11, v3
	s_add_i32 m0, s31, 0x10000
	s_lshr_b32 s0, s4, 8
	global_load_lds_dwordx4 v132, s[36:37]
	s_add_i32 m0, s31, 0x12000
	v_lshl_or_b32 v136, v2, 11, v3
	s_add_u32 s2, s36, 0x40000
	global_load_lds_dwordx4 v136, s[36:37]
	s_addc_u32 s3, s37, 0
	s_add_i32 m0, s31, 0x14000
	s_add_i32 s47, s31, 0x2000
	global_load_lds_dwordx4 v132, s[2:3]
	s_add_i32 m0, s31, 0x16000
	v_lshl_or_b32 v130, v7, 11, v3
	global_load_lds_dwordx4 v136, s[2:3]
	s_mov_b32 m0, s31
	s_add_u32 s2, s34, 0x40000
	v_lshl_or_b32 v134, v4, 11, v3
	global_load_lds_dwordx4 v130, s[34:35]
	s_mov_b32 m0, s47
	s_addc_u32 s3, s35, 0
	s_add_i32 s48, s31, 0x4000
	global_load_lds_dwordx4 v134, s[34:35]
	s_mov_b32 m0, s48
	s_add_i32 s49, s31, 0x6000
	global_load_lds_dwordx4 v130, s[2:3]
	s_mov_b32 m0, s49
	v_mov_b32_e32 v133, 0
	global_load_lds_dwordx4 v134, s[2:3]
	v_mov_b32_e32 v137, v133
	v_mov_b32_e32 v131, v133
	v_mov_b32_e32 v135, v133
	s_cmp_eq_u32 s0, 1
	s_mov_b32 s11, 0
	v_lshl_add_u64 v[8:9], s[36:37], 0, v[132:133]
	v_lshl_add_u64 v[6:7], s[36:37], 0, v[136:137]
	v_lshl_add_u64 v[2:3], s[34:35], 0, v[130:131]
	s_cselect_b64 s[12:13], -1, 0
	s_cmp_lg_u32 s0, 1
	v_lshl_add_u64 v[4:5], s[34:35], 0, v[134:135]
	s_cbranch_scc1 .LBB0_1345
	s_barrier

; __device__ __forceinline__ float silu_f(float x) { return x * __builtin_amdgcn_rcpf(1.0f + __expf(-x)); }
; __device__ __forceinline__ u32x4 pack8(const f32x4 a, const f32x4 b) { u32x4 w; w.x = cvt_pk_bf16(a[0], a[1]); w.y = cvt_pk_bf16(a[2], a[3]); w.z = cvt_pk_bf16(b[0], b[1]); w.w = cvt_pk_bf16(b[2], b[3]); return w; }
; __device__ __forceinline__ float row_rs(const float* part, int row) {
;     const f32x4* p = (const f32x4*)(part + (size_t)row * 16);
;     const f32x4 a = p[0], b = p[1], c = p[2], d = p[3];
;     const float s = (((a[0] + a[1]) + (a[2] + a[3])) + ((b[0] + b[1]) + (b[2] + b[3]))) + (((c[0] + c[1]) + (c[2] + c[3])) + ((d[0] + d[1]) + (d[2] + d[3])));
;     return rsqrtf(s * (1.0f / D) + RMS_EPS);
; }
;     __device__ __forceinline__ void operator()(const Acc& acc, const pg8::Unit& u, int wr, int wc, int fr, int fq) const {
;     ...
;         for (int ai = 0; ai < 2; ++ai)
; #pragma unroll
;             for (int m = 0; m < 4; ++m) {
;                 const int row = u.pm * 256 + ai * 128 + wr * 64 + m * 16 + fr;
;                 const float rs = row_rs(part, row);
;                 const int col = u.pn * 128 + wc * 32 + 8 * fq;
;                 f32x4 h[2];
; #pragma unroll
;                 for (int n = 0; n < 2; ++n)
; #pragma unroll
;                     for (int e = 0; e < 4; ++e) h[n][e] = silu_f(acc[ai][0][m][n][e] * rs) * (acc[ai][1][m][n][e] * rs);
;                 *(u32x4*)(hff + (size_t)row * DFF + col) = pack8(h[0], h[1]);
.LBB0_1370:
	s_waitcnt vmcnt(8)
	v_add_f32_e32 v222, v222, v223
	v_add_f32_e32 v224, v224, v225
	v_add_f32_e32 v226, v226, v227
	v_add_f32_e32 v228, v228, v229
	v_add_f32_e32 v230, v230, v231
	v_add_f32_e32 v232, v232, v233
	v_add_f32_e32 v234, v234, v235
	v_add_f32_e32 v236, v236, v237
	v_add_f32_e32 v238, v238, v239
	v_add_f32_e32 v240, v240, v241
	v_add_f32_e32 v242, v242, v243
	v_add_f32_e32 v244, v244, v245
	v_add_f32_e32 v248, v248, v249
	v_add_f32_e32 v250, v250, v251
	v_add_f32_e32 v252, v252, v253
	v_add_f32_e32 v254, v254, v255
	v_add_f32_e32 v176, v222, v224
	v_add_f32_e32 v177, v226, v228
	v_add_f32_e32 v178, v230, v232
	v_add_f32_e32 v179, v234, v236
	v_add_f32_e32 v180, v238, v240
	v_add_f32_e32 v181, v242, v244
	v_add_f32_e32 v182, v248, v250
	v_add_f32_e32 v183, v252, v254
	v_mov_b32_e32 v184, v176
	v_mov_b32_e32 v185, v177
	v_mov_b32_e32 v186, v178
	v_mov_b32_e32 v187, v179
	v_mov_b32_e32 v188, v180
	v_mov_b32_e32 v189, v181
	v_mov_b32_e32 v190, v182
	v_mov_b32_e32 v191, v183
	v_permlane16_swap_b32_e32 v176, v184
	v_permlane16_swap_b32_e32 v177, v185
	v_permlane16_swap_b32_e32 v178, v186
	v_permlane16_swap_b32_e32 v179, v187
	v_permlane16_swap_b32_e32 v180, v188
	v_permlane16_swap_b32_e32 v181, v189
	v_permlane16_swap_b32_e32 v182, v190
	v_permlane16_swap_b32_e32 v183, v191
	v_add_f32_e32 v176, v176, v184
	v_add_f32_e32 v177, v177, v185
	v_add_f32_e32 v178, v178, v186
	v_add_f32_e32 v179, v179, v187
	v_add_f32_e32 v180, v180, v188
	v_add_f32_e32 v181, v181, v189
	v_add_f32_e32 v182, v182, v190
	v_add_f32_e32 v183, v183, v191
	v_mov_b32_e32 v184, v176
	v_mov_b32_e32 v185, v177
	v_mov_b32_e32 v186, v178
	v_mov_b32_e32 v187, v179
	v_mov_b32_e32 v188, v180
	v_mov_b32_e32 v189, v181
	v_mov_b32_e32 v190, v182
	v_mov_b32_e32 v191, v183
	v_permlane32_swap_b32_e32 v176, v184
	v_permlane32_swap_b32_e32 v177, v185
	v_permlane32_swap_b32_e32 v178, v186
	v_permlane32_swap_b32_e32 v179, v187
	v_permlane32_swap_b32_e32 v180, v188
	v_permlane32_swap_b32_e32 v181, v189
	v_permlane32_swap_b32_e32 v182, v190
	v_permlane32_swap_b32_e32 v183, v191
	v_add_f32_e32 v176, v176, v184
	v_add_f32_e32 v177, v177, v185
	v_add_f32_e32 v178, v178, v186
	v_add_f32_e32 v179, v179, v187
	v_add_f32_e32 v180, v180, v188
	v_add_f32_e32 v181, v181, v189
	v_add_f32_e32 v182, v182, v190
	v_add_f32_e32 v183, v183, v191
	v_fmamk_f32 v176, v176, 0x3a800000, v153
	v_fmamk_f32 v177, v177, 0x3a800000, v153
	v_fmamk_f32 v178, v178, 0x3a800000, v153
	v_fmamk_f32 v179, v179, 0x3a800000, v153
	v_fmamk_f32 v180, v180, 0x3a800000, v153
	v_fmamk_f32 v181, v181, 0x3a800000, v153
	v_fmamk_f32 v182, v182, 0x3a800000, v153
	v_fmamk_f32 v183, v183, 0x3a800000, v153
	v_rsq_f32_e32 v176, v176
	v_rsq_f32_e32 v177, v177
	v_rsq_f32_e32 v178, v178
	v_rsq_f32_e32 v179, v179
	v_rsq_f32_e32 v180, v180
	v_rsq_f32_e32 v181, v181
	v_rsq_f32_e32 v182, v182
	v_rsq_f32_e32 v183, v183
	v_lshl_add_u32 v192, s22, 14, v246
	v_add_u32_e32 v193, 0x2000, v192
	global_load_dwordx4 v[222:225], v192, s[90:91]
	global_load_dwordx4 v[226:229], v192, s[90:91] offset:1024
	global_load_dwordx4 v[230:233], v192, s[90:91] offset:2048
	global_load_dwordx4 v[234:237], v192, s[90:91] offset:3072
	global_load_dwordx4 v[238:241], v193, s[90:91]
	global_load_dwordx4 v[242:245], v193, s[90:91] offset:1024
	global_load_dwordx4 v[248:251], v193, s[90:91] offset:2048
	global_load_dwordx4 v[252:255], v193, s[90:91] offset:3072
	v_lshl_add_u32 v148, s30, 8, v147
	v_ashrrev_i32_e32 v149, 31, v148
	v_lshlrev_b64 v[142:143], 6, v[148:149]
	v_lshl_add_u64 v[142:143], s[90:91], 0, v[142:143]
	v_lshl_or_b32 v144, s28, 7, v151
	v_mov_b64_e32 v[142:143], s[14:15]
	v_ashrrev_i32_e32 v145, 31, v144
	v_mad_i64_i32 v[170:171], s[4:5], v148, s58, v[142:143]
	v_lshlrev_b64 v[144:145], 1, v[144:145]
	v_or_b32_e32 v172, 16, v148
	v_ashrrev_i32_e32 v173, 31, v172
	s_nop 0
	v_lshlrev_b64 v[156:157], 6, v[172:173]
	v_lshl_add_u64 v[156:157], s[90:91], 0, v[156:157]
	s_nop 0
	v_lshl_add_u64 v[154:155], v[170:171], 0, v[144:145]
	v_mov_b32_e32 v158, v176
	v_pk_mul_f32 v[126:127], v[126:127], v[158:159] op_sel_hi:[1,0]
	v_pk_mul_f32 v[128:129], v[128:129], v[158:159] op_sel_hi:[1,0]
	v_pk_mul_f32 v[122:123], v[122:123], v[158:159] op_sel_hi:[1,0]
	v_pk_mul_f32 v[124:125], v[124:125], v[158:159] op_sel_hi:[1,0]
	v_pk_mul_f32 v[118:119], v[118:119], v[158:159] op_sel_hi:[1,0]
	v_pk_mul_f32 v[120:121], v[120:121], v[158:159] op_sel_hi:[1,0]
	v_pk_mul_f32 v[114:115], v[114:115], v[158:159] op_sel_hi:[1,0]
	v_pk_mul_f32 v[116:117], v[116:117], v[158:159] op_sel_hi:[1,0]
	v_mul_f32_e32 v149, 0xbfb8aa3b, v126
	v_mul_f32_e32 v158, 0xbfb8aa3b, v127
	v_mul_f32_e32 v159, 0xbfb8aa3b, v128
	v_mul_f32_e32 v160, 0xbfb8aa3b, v129
	v_mul_f32_e32 v161, 0xbfb8aa3b, v122
	v_mul_f32_e32 v162, 0xbfb8aa3b, v123
	v_mul_f32_e32 v163, 0xbfb8aa3b, v124
	v_mul_f32_e32 v164, 0xbfb8aa3b, v125
	v_exp_f32_e32 v149, v149
	v_exp_f32_e32 v158, v158
	v_exp_f32_e32 v159, v159
	v_exp_f32_e32 v160, v160
	v_exp_f32_e32 v161, v161
	v_exp_f32_e32 v162, v162
	v_exp_f32_e32 v163, v163
	v_exp_f32_e32 v164, v164
	v_add_f32_e32 v149, 1.0, v149
	v_add_f32_e32 v165, 1.0, v158
	v_add_f32_e32 v166, 1.0, v159
	v_add_f32_e32 v167, 1.0, v160
	v_add_f32_e32 v168, 1.0, v161
	v_add_f32_e32 v169, 1.0, v162
	v_add_f32_e32 v170, 1.0, v163
	v_add_f32_e32 v171, 1.0, v164
	v_rcp_f32_e32 v158, v149
	v_rcp_f32_e32 v159, v165
	v_rcp_f32_e32 v160, v166
	v_rcp_f32_e32 v161, v167
	v_rcp_f32_e32 v162, v168
	v_rcp_f32_e32 v163, v169
	v_rcp_f32_e32 v164, v170
	v_rcp_f32_e32 v165, v171
	v_pk_mul_f32 v[126:127], v[126:127], v[158:159]
	v_pk_mul_f32 v[128:129], v[128:129], v[160:161]
	v_pk_mul_f32 v[122:123], v[122:123], v[162:163]
; __device__ __forceinline__ float silu_f(float x) { return x * __builtin_amdgcn_rcpf(1.0f + __expf(-x)); }
; __device__ __forceinline__ u32x4 pack8(const f32x4 a, const f32x4 b) { u32x4 w; w.x = cvt_pk_bf16(a[0], a[1]); w.y = cvt_pk_bf16(a[2], a[3]); w.z = cvt_pk_bf16(b[0], b[1]); w.w = cvt_pk_bf16(b[2], b[3]); return w; }
;     __device__ __forceinline__ void operator()(const Acc& acc, const pg8::Unit& u, int wr, int wc, int fr, int fq) const {
;     ...
;         for (int ai = 0; ai < 2; ++ai)
; #pragma unroll
;             for (int m = 0; m < 4; ++m) {
;                 const int row = u.pm * 256 + ai * 128 + wr * 64 + m * 16 + fr;
;                 const float rs = row_rs(part, row);
;                 const int col = u.pn * 128 + wc * 32 + 8 * fq;
;                 f32x4 h[2];
; #pragma unroll
;                 for (int n = 0; n < 2; ++n)
; #pragma unroll
;                     for (int e = 0; e < 4; ++e) h[n][e] = silu_f(acc[ai][0][m][n][e] * rs) * (acc[ai][1][m][n][e] * rs);
;                 *(u32x4*)(hff + (size_t)row * DFF + col) = pack8(h[0], h[1]);
	v_pk_mul_f32 v[124:125], v[124:125], v[164:165]
	v_pk_mul_f32 v[118:119], v[118:119], v[126:127]
	v_pk_mul_f32 v[120:121], v[120:121], v[128:129]
	v_pk_mul_f32 v[122:123], v[114:115], v[122:123]
	v_pk_mul_f32 v[124:125], v[116:117], v[124:125]
	v_cvt_pk_bf16_f32 v114, v118, v119
	v_cvt_pk_bf16_f32 v115, v120, v121
	v_cvt_pk_bf16_f32 v116, v122, v123
	v_cvt_pk_bf16_f32 v117, v124, v125
	global_store_dwordx4 v[154:155], v[114:117], off
	s_nop 0
	v_or_b32_e32 v154, 32, v148
	v_mad_i64_i32 v[156:157], s[4:5], v172, s58, v[142:143]
	v_ashrrev_i32_e32 v155, 31, v154
	s_nop 0
	v_lshlrev_b64 v[116:117], 6, v[154:155]
	v_lshl_add_u64 v[116:117], s[90:91], 0, v[116:117]
	s_nop 0
	v_lshl_add_u64 v[114:115], v[156:157], 0, v[144:145]
	v_mov_b32_e32 v118, v177
	v_pk_mul_f32 v[110:111], v[110:111], v[118:119] op_sel_hi:[1,0]
	v_pk_mul_f32 v[112:113], v[112:113], v[118:119] op_sel_hi:[1,0]
	v_pk_mul_f32 v[106:107], v[106:107], v[118:119] op_sel_hi:[1,0]
	v_pk_mul_f32 v[108:109], v[108:109], v[118:119] op_sel_hi:[1,0]
	v_pk_mul_f32 v[102:103], v[102:103], v[118:119] op_sel_hi:[1,0]
	v_pk_mul_f32 v[104:105], v[104:105], v[118:119] op_sel_hi:[1,0]
	v_pk_mul_f32 v[98:99], v[98:99], v[118:119] op_sel_hi:[1,0]
	v_pk_mul_f32 v[100:101], v[100:101], v[118:119] op_sel_hi:[1,0]
	v_mul_f32_e32 v118, 0xbfb8aa3b, v110
	v_mul_f32_e32 v119, 0xbfb8aa3b, v111
	v_mul_f32_e32 v120, 0xbfb8aa3b, v112
	v_mul_f32_e32 v121, 0xbfb8aa3b, v113
	v_mul_f32_e32 v122, 0xbfb8aa3b, v106
	v_mul_f32_e32 v123, 0xbfb8aa3b, v107
	v_mul_f32_e32 v124, 0xbfb8aa3b, v108
	v_mul_f32_e32 v125, 0xbfb8aa3b, v109
	v_exp_f32_e32 v118, v118
	v_exp_f32_e32 v119, v119
	v_exp_f32_e32 v120, v120
	v_exp_f32_e32 v121, v121
	v_exp_f32_e32 v122, v122
	v_exp_f32_e32 v123, v123
	v_exp_f32_e32 v124, v124
	v_exp_f32_e32 v125, v125
	v_add_f32_e32 v118, 1.0, v118
	v_add_f32_e32 v119, 1.0, v119
	v_add_f32_e32 v120, 1.0, v120
	v_add_f32_e32 v121, 1.0, v121
	v_add_f32_e32 v122, 1.0, v122
	v_add_f32_e32 v123, 1.0, v123
	v_add_f32_e32 v124, 1.0, v124
	v_add_f32_e32 v125, 1.0, v125
	v_rcp_f32_e32 v118, v118
	v_rcp_f32_e32 v119, v119
	v_rcp_f32_e32 v120, v120
	v_rcp_f32_e32 v121, v121
	v_rcp_f32_e32 v122, v122
	v_rcp_f32_e32 v123, v123
	v_rcp_f32_e32 v124, v124
	v_rcp_f32_e32 v125, v125
	v_pk_mul_f32 v[110:111], v[110:111], v[118:119]
	v_pk_mul_f32 v[112:113], v[112:113], v[120:121]
	v_pk_mul_f32 v[106:107], v[106:107], v[122:123]
	v_pk_mul_f32 v[108:109], v[108:109], v[124:125]
	v_pk_mul_f32 v[102:103], v[102:103], v[110:111]
	v_pk_mul_f32 v[104:105], v[104:105], v[112:113]
	v_pk_mul_f32 v[106:107], v[98:99], v[106:107]
	v_pk_mul_f32 v[108:109], v[100:101], v[108:109]
	v_cvt_pk_bf16_f32 v98, v102, v103
	v_cvt_pk_bf16_f32 v99, v104, v105
	v_cvt_pk_bf16_f32 v100, v106, v107
	v_cvt_pk_bf16_f32 v101, v108, v109
	global_store_dwordx4 v[114:115], v[98:101], off
	s_nop 0
	v_or_b32_e32 v114, 48, v148
	v_mad_i64_i32 v[116:117], s[4:5], v154, s58, v[142:143]
	v_ashrrev_i32_e32 v115, 31, v114
	s_nop 0
	v_lshlrev_b64 v[100:101], 6, v[114:115]
	v_lshl_add_u64 v[100:101], s[90:91], 0, v[100:101]
	s_nop 0
	v_lshl_add_u64 v[98:99], v[116:117], 0, v[144:145]
	v_mov_b32_e32 v102, v178
	v_pk_mul_f32 v[94:95], v[94:95], v[102:103] op_sel_hi:[1,0]
	v_pk_mul_f32 v[96:97], v[96:97], v[102:103] op_sel_hi:[1,0]
	v_pk_mul_f32 v[90:91], v[90:91], v[102:103] op_sel_hi:[1,0]
	v_pk_mul_f32 v[92:93], v[92:93], v[102:103] op_sel_hi:[1,0]
	v_pk_mul_f32 v[86:87], v[86:87], v[102:103] op_sel_hi:[1,0]
	v_pk_mul_f32 v[88:89], v[88:89], v[102:103] op_sel_hi:[1,0]
	v_pk_mul_f32 v[82:83], v[82:83], v[102:103] op_sel_hi:[1,0]
	v_pk_mul_f32 v[84:85], v[84:85], v[102:103] op_sel_hi:[1,0]
	v_mul_f32_e32 v102, 0xbfb8aa3b, v94
	v_mul_f32_e32 v103, 0xbfb8aa3b, v95
	v_mul_f32_e32 v104, 0xbfb8aa3b, v96
	v_mul_f32_e32 v105, 0xbfb8aa3b, v97
	v_mul_f32_e32 v106, 0xbfb8aa3b, v90
	v_mul_f32_e32 v107, 0xbfb8aa3b, v91
	v_mul_f32_e32 v108, 0xbfb8aa3b, v92
	v_mul_f32_e32 v109, 0xbfb8aa3b, v93
	v_exp_f32_e32 v102, v102
	v_exp_f32_e32 v103, v103
	v_exp_f32_e32 v104, v104
	v_exp_f32_e32 v105, v105
	v_exp_f32_e32 v106, v106
	v_exp_f32_e32 v107, v107
	v_exp_f32_e32 v108, v108
	v_exp_f32_e32 v109, v109
	v_add_f32_e32 v102, 1.0, v102
	v_add_f32_e32 v103, 1.0, v103
	v_add_f32_e32 v104, 1.0, v104
	v_add_f32_e32 v105, 1.0, v105
	v_add_f32_e32 v106, 1.0, v106
	v_add_f32_e32 v107, 1.0, v107
	v_add_f32_e32 v108, 1.0, v108
	v_add_f32_e32 v109, 1.0, v109
	v_rcp_f32_e32 v102, v102
	v_rcp_f32_e32 v103, v103
	v_rcp_f32_e32 v104, v104
	v_rcp_f32_e32 v105, v105
	v_rcp_f32_e32 v106, v106
	v_rcp_f32_e32 v107, v107
	v_rcp_f32_e32 v108, v108
	v_rcp_f32_e32 v109, v109
	v_pk_mul_f32 v[94:95], v[94:95], v[102:103]
	v_pk_mul_f32 v[96:97], v[96:97], v[104:105]
	v_pk_mul_f32 v[90:91], v[90:91], v[106:107]
	v_pk_mul_f32 v[92:93], v[92:93], v[108:109]
	v_pk_mul_f32 v[86:87], v[86:87], v[94:95]
	v_pk_mul_f32 v[88:89], v[88:89], v[96:97]
	v_pk_mul_f32 v[90:91], v[82:83], v[90:91]
	v_pk_mul_f32 v[92:93], v[84:85], v[92:93]
	v_cvt_pk_bf16_f32 v82, v86, v87
	v_cvt_pk_bf16_f32 v83, v88, v89
	v_cvt_pk_bf16_f32 v84, v90, v91
	v_cvt_pk_bf16_f32 v85, v92, v93
	global_store_dwordx4 v[98:99], v[82:85], off
	s_nop 0
	v_add_u32_e32 v98, 0x80, v148
	v_mad_i64_i32 v[100:101], s[4:5], v114, s58, v[142:143]
	v_ashrrev_i32_e32 v99, 31, v98
	s_nop 0
	v_lshlrev_b64 v[84:85], 6, v[98:99]
	v_lshl_add_u64 v[84:85], s[90:91], 0, v[84:85]
	s_nop 0
	v_lshl_add_u64 v[82:83], v[100:101], 0, v[144:145]
	v_mov_b32_e32 v86, v179
	v_pk_mul_f32 v[78:79], v[78:79], v[86:87] op_sel_hi:[1,0]
	v_pk_mul_f32 v[80:81], v[80:81], v[86:87] op_sel_hi:[1,0]
	v_pk_mul_f32 v[74:75], v[74:75], v[86:87] op_sel_hi:[1,0]
	v_pk_mul_f32 v[76:77], v[76:77], v[86:87] op_sel_hi:[1,0]
; __device__ __forceinline__ float silu_f(float x) { return x * __builtin_amdgcn_rcpf(1.0f + __expf(-x)); }
; __device__ __forceinline__ u32x4 pack8(const f32x4 a, const f32x4 b) { u32x4 w; w.x = cvt_pk_bf16(a[0], a[1]); w.y = cvt_pk_bf16(a[2], a[3]); w.z = cvt_pk_bf16(b[0], b[1]); w.w = cvt_pk_bf16(b[2], b[3]); return w; }
;     __device__ __forceinline__ void operator()(const Acc& acc, const pg8::Unit& u, int wr, int wc, int fr, int fq) const {
;     ...
;         for (int ai = 0; ai < 2; ++ai)
; #pragma unroll
;             for (int m = 0; m < 4; ++m) {
;                 const int row = u.pm * 256 + ai * 128 + wr * 64 + m * 16 + fr;
;                 const float rs = row_rs(part, row);
;                 const int col = u.pn * 128 + wc * 32 + 8 * fq;
;                 f32x4 h[2];
; #pragma unroll
;                 for (int n = 0; n < 2; ++n)
; #pragma unroll
;                     for (int e = 0; e < 4; ++e) h[n][e] = silu_f(acc[ai][0][m][n][e] * rs) * (acc[ai][1][m][n][e] * rs);
;                 *(u32x4*)(hff + (size_t)row * DFF + col) = pack8(h[0], h[1]);
	v_pk_mul_f32 v[70:71], v[70:71], v[86:87] op_sel_hi:[1,0]
	v_pk_mul_f32 v[72:73], v[72:73], v[86:87] op_sel_hi:[1,0]
	v_pk_mul_f32 v[66:67], v[66:67], v[86:87] op_sel_hi:[1,0]
	v_pk_mul_f32 v[68:69], v[68:69], v[86:87] op_sel_hi:[1,0]
	v_mul_f32_e32 v86, 0xbfb8aa3b, v78
	v_mul_f32_e32 v87, 0xbfb8aa3b, v79
	v_mul_f32_e32 v88, 0xbfb8aa3b, v80
	v_mul_f32_e32 v89, 0xbfb8aa3b, v81
	v_mul_f32_e32 v90, 0xbfb8aa3b, v74
	v_mul_f32_e32 v91, 0xbfb8aa3b, v75
	v_mul_f32_e32 v92, 0xbfb8aa3b, v76
	v_mul_f32_e32 v93, 0xbfb8aa3b, v77
	v_exp_f32_e32 v86, v86
	v_exp_f32_e32 v87, v87
	v_exp_f32_e32 v88, v88
	v_exp_f32_e32 v89, v89
	v_exp_f32_e32 v90, v90
	v_exp_f32_e32 v91, v91
	v_exp_f32_e32 v92, v92
	v_exp_f32_e32 v93, v93
	v_add_f32_e32 v86, 1.0, v86
	v_add_f32_e32 v87, 1.0, v87
	v_add_f32_e32 v88, 1.0, v88
	v_add_f32_e32 v89, 1.0, v89
	v_add_f32_e32 v90, 1.0, v90
	v_add_f32_e32 v91, 1.0, v91
	v_add_f32_e32 v92, 1.0, v92
	v_add_f32_e32 v93, 1.0, v93
	v_rcp_f32_e32 v86, v86
	v_rcp_f32_e32 v87, v87
	v_rcp_f32_e32 v88, v88
	v_rcp_f32_e32 v89, v89
	v_rcp_f32_e32 v90, v90
	v_rcp_f32_e32 v91, v91
	v_rcp_f32_e32 v92, v92
	v_rcp_f32_e32 v93, v93
	v_pk_mul_f32 v[78:79], v[78:79], v[86:87]
	v_pk_mul_f32 v[80:81], v[80:81], v[88:89]
	v_pk_mul_f32 v[74:75], v[74:75], v[90:91]
	v_pk_mul_f32 v[76:77], v[76:77], v[92:93]
	v_pk_mul_f32 v[70:71], v[70:71], v[78:79]
	v_pk_mul_f32 v[72:73], v[72:73], v[80:81]
	v_pk_mul_f32 v[74:75], v[66:67], v[74:75]
	v_pk_mul_f32 v[76:77], v[68:69], v[76:77]
	v_cvt_pk_bf16_f32 v66, v70, v71
	v_cvt_pk_bf16_f32 v67, v72, v73
	v_cvt_pk_bf16_f32 v68, v74, v75
	v_cvt_pk_bf16_f32 v69, v76, v77
	global_store_dwordx4 v[82:83], v[66:69], off
	s_nop 0
	v_add_u32_e32 v82, 0x90, v148
	v_mad_i64_i32 v[84:85], s[4:5], v98, s58, v[142:143]
	v_ashrrev_i32_e32 v83, 31, v82
	s_nop 0
	v_lshlrev_b64 v[68:69], 6, v[82:83]
	v_lshl_add_u64 v[68:69], s[90:91], 0, v[68:69]
	s_nop 0
	v_lshl_add_u64 v[66:67], v[84:85], 0, v[144:145]
	v_mov_b32_e32 v70, v180
	v_pk_mul_f32 v[62:63], v[62:63], v[70:71] op_sel_hi:[1,0]
	v_pk_mul_f32 v[64:65], v[64:65], v[70:71] op_sel_hi:[1,0]
	v_pk_mul_f32 v[58:59], v[58:59], v[70:71] op_sel_hi:[1,0]
	v_pk_mul_f32 v[60:61], v[60:61], v[70:71] op_sel_hi:[1,0]
	v_pk_mul_f32 v[54:55], v[54:55], v[70:71] op_sel_hi:[1,0]
	v_pk_mul_f32 v[56:57], v[56:57], v[70:71] op_sel_hi:[1,0]
	v_pk_mul_f32 v[50:51], v[50:51], v[70:71] op_sel_hi:[1,0]
	v_pk_mul_f32 v[52:53], v[52:53], v[70:71] op_sel_hi:[1,0]
	v_mul_f32_e32 v70, 0xbfb8aa3b, v62
	v_mul_f32_e32 v71, 0xbfb8aa3b, v63
	v_mul_f32_e32 v72, 0xbfb8aa3b, v64
	v_mul_f32_e32 v73, 0xbfb8aa3b, v65
	v_mul_f32_e32 v74, 0xbfb8aa3b, v58
	v_mul_f32_e32 v75, 0xbfb8aa3b, v59
	v_mul_f32_e32 v76, 0xbfb8aa3b, v60
	v_mul_f32_e32 v77, 0xbfb8aa3b, v61
	v_exp_f32_e32 v70, v70
	v_exp_f32_e32 v71, v71
	v_exp_f32_e32 v72, v72
	v_exp_f32_e32 v73, v73
	v_exp_f32_e32 v74, v74
	v_exp_f32_e32 v75, v75
	v_exp_f32_e32 v76, v76
	v_exp_f32_e32 v77, v77
	v_add_f32_e32 v70, 1.0, v70
	v_add_f32_e32 v71, 1.0, v71
	v_add_f32_e32 v72, 1.0, v72
	v_add_f32_e32 v73, 1.0, v73
	v_add_f32_e32 v74, 1.0, v74
	v_add_f32_e32 v75, 1.0, v75
	v_add_f32_e32 v76, 1.0, v76
	v_add_f32_e32 v77, 1.0, v77
	v_rcp_f32_e32 v70, v70
	v_rcp_f32_e32 v71, v71
	v_rcp_f32_e32 v72, v72
	v_rcp_f32_e32 v73, v73
	v_rcp_f32_e32 v74, v74
	v_rcp_f32_e32 v75, v75
	v_rcp_f32_e32 v76, v76
	v_rcp_f32_e32 v77, v77
	v_pk_mul_f32 v[62:63], v[62:63], v[70:71]
	v_pk_mul_f32 v[64:65], v[64:65], v[72:73]
	v_pk_mul_f32 v[58:59], v[58:59], v[74:75]
	v_pk_mul_f32 v[60:61], v[60:61], v[76:77]
	v_pk_mul_f32 v[54:55], v[54:55], v[62:63]
	v_pk_mul_f32 v[56:57], v[56:57], v[64:65]
	v_pk_mul_f32 v[58:59], v[50:51], v[58:59]
	v_pk_mul_f32 v[60:61], v[52:53], v[60:61]
	v_cvt_pk_bf16_f32 v50, v54, v55
	v_cvt_pk_bf16_f32 v51, v56, v57
	v_cvt_pk_bf16_f32 v52, v58, v59
	v_cvt_pk_bf16_f32 v53, v60, v61
	global_store_dwordx4 v[66:67], v[50:53], off
	s_nop 0
	v_add_u32_e32 v66, 0xa0, v148
	v_mad_i64_i32 v[68:69], s[4:5], v82, s58, v[142:143]
	v_ashrrev_i32_e32 v67, 31, v66
	s_nop 0
	v_lshlrev_b64 v[52:53], 6, v[66:67]
	v_lshl_add_u64 v[52:53], s[90:91], 0, v[52:53]
	s_nop 0
	v_lshl_add_u64 v[50:51], v[68:69], 0, v[144:145]
	v_mov_b32_e32 v54, v181
	v_pk_mul_f32 v[46:47], v[46:47], v[54:55] op_sel_hi:[1,0]
	v_pk_mul_f32 v[48:49], v[48:49], v[54:55] op_sel_hi:[1,0]
	v_pk_mul_f32 v[42:43], v[42:43], v[54:55] op_sel_hi:[1,0]
	v_pk_mul_f32 v[44:45], v[44:45], v[54:55] op_sel_hi:[1,0]
	v_pk_mul_f32 v[38:39], v[38:39], v[54:55] op_sel_hi:[1,0]
	v_pk_mul_f32 v[40:41], v[40:41], v[54:55] op_sel_hi:[1,0]
	v_pk_mul_f32 v[34:35], v[34:35], v[54:55] op_sel_hi:[1,0]
	v_pk_mul_f32 v[36:37], v[36:37], v[54:55] op_sel_hi:[1,0]
	v_mul_f32_e32 v54, 0xbfb8aa3b, v46
	v_mul_f32_e32 v55, 0xbfb8aa3b, v47
	v_mul_f32_e32 v56, 0xbfb8aa3b, v48
	v_mul_f32_e32 v57, 0xbfb8aa3b, v49
	v_mul_f32_e32 v58, 0xbfb8aa3b, v42
	v_mul_f32_e32 v59, 0xbfb8aa3b, v43
	v_mul_f32_e32 v60, 0xbfb8aa3b, v44
	v_mul_f32_e32 v61, 0xbfb8aa3b, v45
	v_exp_f32_e32 v54, v54
	v_exp_f32_e32 v55, v55
	v_exp_f32_e32 v56, v56
	v_exp_f32_e32 v57, v57
	v_exp_f32_e32 v58, v58
	v_exp_f32_e32 v59, v59
	v_exp_f32_e32 v60, v60
	v_exp_f32_e32 v61, v61
	v_add_f32_e32 v54, 1.0, v54
	v_add_f32_e32 v55, 1.0, v55
	v_add_f32_e32 v56, 1.0, v56
	v_add_f32_e32 v57, 1.0, v57
; __device__ __forceinline__ float silu_f(float x) { return x * __builtin_amdgcn_rcpf(1.0f + __expf(-x)); }
; __device__ __forceinline__ u32x4 pack8(const f32x4 a, const f32x4 b) { u32x4 w; w.x = cvt_pk_bf16(a[0], a[1]); w.y = cvt_pk_bf16(a[2], a[3]); w.z = cvt_pk_bf16(b[0], b[1]); w.w = cvt_pk_bf16(b[2], b[3]); return w; }
; template <class Epi, class Sched, bool ALIGN_EPI = false, bool SP2 = false>
; __device__ __forceinline__ void gemm_phase(PG8_LAS unsigned char* lds, const Gemm g, const Sched& S, const Epi& E) {
;     ...
;     for (;;) {
;         const bool has_next = S.next(ui + 1, nxt);
;         const char* nA = has_next ? (const char*)g.A + (size_t)nxt.pm * tstep + (size_t)nxt.kt0 * kstep : cA; const char* nB = has_next ? (const char*)g.Bt + (size_t)nxt.pn * tstep + (size_t)nxt.kt0 * kstep : cB;
;         const int nt = cur.nt;
;         for (int t = 0; t < nt; t += 2) {
;     __device__ __forceinline__ void operator()(const Acc& acc, const pg8::Unit& u, int wr, int wc, int fr, int fq) const {
;     ...
;         for (int ai = 0; ai < 2; ++ai)
; #pragma unroll
;             for (int m = 0; m < 4; ++m) {
;                 const int row = u.pm * 256 + ai * 128 + wr * 64 + m * 16 + fr;
;                 const float rs = row_rs(part, row);
;                 const int col = u.pn * 128 + wc * 32 + 8 * fq;
;                 f32x4 h[2];
; #pragma unroll
;                 for (int n = 0; n < 2; ++n)
; #pragma unroll
;                     for (int e = 0; e < 4; ++e) h[n][e] = silu_f(acc[ai][0][m][n][e] * rs) * (acc[ai][1][m][n][e] * rs);
;                 *(u32x4*)(hff + (size_t)row * DFF + col) = pack8(h[0], h[1]);
	v_add_f32_e32 v58, 1.0, v58
	v_add_f32_e32 v59, 1.0, v59
	v_add_f32_e32 v60, 1.0, v60
	v_add_f32_e32 v61, 1.0, v61
	v_rcp_f32_e32 v54, v54
	v_rcp_f32_e32 v55, v55
	v_rcp_f32_e32 v56, v56
	v_rcp_f32_e32 v57, v57
	v_rcp_f32_e32 v58, v58
	v_rcp_f32_e32 v59, v59
	v_rcp_f32_e32 v60, v60
	v_rcp_f32_e32 v61, v61
	v_pk_mul_f32 v[46:47], v[46:47], v[54:55]
	v_pk_mul_f32 v[48:49], v[48:49], v[56:57]
	v_pk_mul_f32 v[42:43], v[42:43], v[58:59]
	v_pk_mul_f32 v[44:45], v[44:45], v[60:61]
	v_pk_mul_f32 v[38:39], v[38:39], v[46:47]
	v_pk_mul_f32 v[40:41], v[40:41], v[48:49]
	v_pk_mul_f32 v[42:43], v[34:35], v[42:43]
	v_pk_mul_f32 v[44:45], v[36:37], v[44:45]
	v_cvt_pk_bf16_f32 v34, v38, v39
	v_cvt_pk_bf16_f32 v35, v40, v41
	v_cvt_pk_bf16_f32 v36, v42, v43
	v_cvt_pk_bf16_f32 v37, v44, v45
	global_store_dwordx4 v[50:51], v[34:37], off
	s_nop 0
	v_add_u32_e32 v50, 0xb0, v148
	v_mad_i64_i32 v[52:53], s[4:5], v66, s58, v[142:143]
	v_ashrrev_i32_e32 v51, 31, v50
	s_nop 0
	v_lshlrev_b64 v[36:37], 6, v[50:51]
	v_lshl_add_u64 v[36:37], s[90:91], 0, v[36:37]
	s_nop 0
	v_lshl_add_u64 v[34:35], v[52:53], 0, v[144:145]
	v_mov_b32_e32 v38, v182
	v_pk_mul_f32 v[30:31], v[30:31], v[38:39] op_sel_hi:[1,0]
	v_pk_mul_f32 v[32:33], v[32:33], v[38:39] op_sel_hi:[1,0]
	v_pk_mul_f32 v[26:27], v[26:27], v[38:39] op_sel_hi:[1,0]
	v_pk_mul_f32 v[28:29], v[28:29], v[38:39] op_sel_hi:[1,0]
	v_pk_mul_f32 v[22:23], v[22:23], v[38:39] op_sel_hi:[1,0]
	v_pk_mul_f32 v[24:25], v[24:25], v[38:39] op_sel_hi:[1,0]
	v_pk_mul_f32 v[18:19], v[18:19], v[38:39] op_sel_hi:[1,0]
	v_pk_mul_f32 v[20:21], v[20:21], v[38:39] op_sel_hi:[1,0]
	v_mul_f32_e32 v38, 0xbfb8aa3b, v30
	v_mul_f32_e32 v39, 0xbfb8aa3b, v31
	v_mul_f32_e32 v40, 0xbfb8aa3b, v32
	v_mul_f32_e32 v41, 0xbfb8aa3b, v33
	v_mul_f32_e32 v42, 0xbfb8aa3b, v26
	v_mul_f32_e32 v43, 0xbfb8aa3b, v27
	v_mul_f32_e32 v44, 0xbfb8aa3b, v28
	v_mul_f32_e32 v45, 0xbfb8aa3b, v29
	v_exp_f32_e32 v38, v38
	v_exp_f32_e32 v39, v39
	v_exp_f32_e32 v40, v40
	v_exp_f32_e32 v41, v41
	v_exp_f32_e32 v42, v42
	v_exp_f32_e32 v43, v43
	v_exp_f32_e32 v44, v44
	v_exp_f32_e32 v45, v45
	v_add_f32_e32 v38, 1.0, v38
	v_add_f32_e32 v39, 1.0, v39
	v_add_f32_e32 v40, 1.0, v40
	v_add_f32_e32 v41, 1.0, v41
	v_add_f32_e32 v42, 1.0, v42
	v_add_f32_e32 v43, 1.0, v43
	v_add_f32_e32 v44, 1.0, v44
	v_add_f32_e32 v45, 1.0, v45
	v_rcp_f32_e32 v38, v38
	v_rcp_f32_e32 v39, v39
	v_rcp_f32_e32 v40, v40
	v_rcp_f32_e32 v41, v41
	v_rcp_f32_e32 v42, v42
	v_rcp_f32_e32 v43, v43
	v_rcp_f32_e32 v44, v44
	v_rcp_f32_e32 v45, v45
	v_pk_mul_f32 v[30:31], v[30:31], v[38:39]
	v_pk_mul_f32 v[32:33], v[32:33], v[40:41]
	v_pk_mul_f32 v[26:27], v[26:27], v[42:43]
	v_pk_mul_f32 v[28:29], v[28:29], v[44:45]
	v_pk_mul_f32 v[22:23], v[22:23], v[30:31]
	v_pk_mul_f32 v[24:25], v[24:25], v[32:33]
	v_pk_mul_f32 v[26:27], v[18:19], v[26:27]
	v_pk_mul_f32 v[28:29], v[20:21], v[28:29]
	v_cvt_pk_bf16_f32 v18, v22, v23
	v_cvt_pk_bf16_f32 v19, v24, v25
	v_cvt_pk_bf16_f32 v20, v26, v27
	v_cvt_pk_bf16_f32 v21, v28, v29
	global_store_dwordx4 v[34:35], v[18:21], off
	s_nop 0
	s_andn2_b64 vcc, exec, s[2:3]
	s_mov_b64 s[2:3], -1
	s_nop 0
	s_nop 0
	s_nop 1
	v_mad_i64_i32 v[18:19], s[34:35], v50, s58, v[142:143]
	v_lshl_add_u64 v[18:19], v[18:19], 0, v[144:145]
	v_mov_b32_e32 v20, v183
	v_pk_mul_f32 v[14:15], v[14:15], v[20:21] op_sel_hi:[1,0]
	v_pk_mul_f32 v[16:17], v[16:17], v[20:21] op_sel_hi:[1,0]
	v_pk_mul_f32 v[10:11], v[10:11], v[20:21] op_sel_hi:[1,0]
	v_pk_mul_f32 v[12:13], v[12:13], v[20:21] op_sel_hi:[1,0]
	v_pk_mul_f32 v[6:7], v[6:7], v[20:21] op_sel_hi:[1,0]
	v_pk_mul_f32 v[8:9], v[8:9], v[20:21] op_sel_hi:[1,0]
	v_pk_mul_f32 v[2:3], v[2:3], v[20:21] op_sel_hi:[1,0]
	v_pk_mul_f32 v[4:5], v[4:5], v[20:21] op_sel_hi:[1,0]
	v_mul_f32_e32 v20, 0xbfb8aa3b, v14
	v_mul_f32_e32 v21, 0xbfb8aa3b, v15
	v_mul_f32_e32 v22, 0xbfb8aa3b, v16
	v_mul_f32_e32 v23, 0xbfb8aa3b, v17
	v_mul_f32_e32 v24, 0xbfb8aa3b, v10
	v_mul_f32_e32 v25, 0xbfb8aa3b, v11
	v_mul_f32_e32 v26, 0xbfb8aa3b, v12
	v_mul_f32_e32 v27, 0xbfb8aa3b, v13
	v_exp_f32_e32 v20, v20
	v_exp_f32_e32 v21, v21
	v_exp_f32_e32 v22, v22
	v_exp_f32_e32 v23, v23
	v_exp_f32_e32 v24, v24
	v_exp_f32_e32 v25, v25
	v_exp_f32_e32 v26, v26
	v_exp_f32_e32 v27, v27
	v_add_f32_e32 v20, 1.0, v20
	v_add_f32_e32 v21, 1.0, v21
	v_add_f32_e32 v22, 1.0, v22
	v_add_f32_e32 v23, 1.0, v23
	v_add_f32_e32 v24, 1.0, v24
	v_add_f32_e32 v25, 1.0, v25
	v_add_f32_e32 v26, 1.0, v26
	v_add_f32_e32 v27, 1.0, v27
	v_rcp_f32_e32 v20, v20
	v_rcp_f32_e32 v21, v21
	v_rcp_f32_e32 v22, v22
	v_rcp_f32_e32 v23, v23
	v_rcp_f32_e32 v24, v24
	v_rcp_f32_e32 v25, v25
	v_rcp_f32_e32 v26, v26
	v_rcp_f32_e32 v27, v27
	v_pk_mul_f32 v[14:15], v[14:15], v[20:21]
	v_pk_mul_f32 v[16:17], v[16:17], v[22:23]
	v_pk_mul_f32 v[10:11], v[10:11], v[24:25]
	v_pk_mul_f32 v[12:13], v[12:13], v[26:27]
	v_pk_mul_f32 v[6:7], v[6:7], v[14:15]
	v_pk_mul_f32 v[8:9], v[8:9], v[16:17]
	v_pk_mul_f32 v[10:11], v[2:3], v[10:11]
	v_pk_mul_f32 v[12:13], v[4:5], v[12:13]
	v_cvt_pk_bf16_f32 v2, v6, v7
	v_cvt_pk_bf16_f32 v3, v8, v9
	v_cvt_pk_bf16_f32 v4, v10, v11
	v_cvt_pk_bf16_f32 v5, v12, v13
	global_store_dwordx4 v[18:19], v[2:5], off
	s_cbranch_vccnz .LBB0_1347
	s_andn2_b64 vcc, exec, s[12:13]
	s_cbranch_vccnz .LBB0_1346
	s_barrier
	s_branch .LBB0_1346

; __global__ void __launch_bounds__(NTHREADS, 2) mega_fwd(Params p) {
	.amdhsa_kernel _Z8mega_fwd6Params
		.amdhsa_group_segment_fixed_size 0
		.amdhsa_private_segment_fixed_size 0
		.amdhsa_kernarg_size 408
		.amdhsa_user_sgpr_count 2
		.amdhsa_user_sgpr_dispatch_ptr 0
		.amdhsa_user_sgpr_queue_ptr 0
		.amdhsa_user_sgpr_kernarg_segment_ptr 1
		.amdhsa_user_sgpr_dispatch_id 0
		.amdhsa_user_sgpr_kernarg_preload_length 0
		.amdhsa_user_sgpr_kernarg_preload_offset 0
		.amdhsa_user_sgpr_private_segment_size 0
		.amdhsa_uses_dynamic_stack 0
		.amdhsa_enable_private_segment 0
		.amdhsa_system_sgpr_workgroup_id_x 1
		.amdhsa_system_sgpr_workgroup_id_y 0
		.amdhsa_system_sgpr_workgroup_id_z 0
		.amdhsa_system_sgpr_workgroup_info 0
		.amdhsa_system_vgpr_workitem_id 2
		.amdhsa_next_free_vgpr 256
		.amdhsa_next_free_sgpr 98
		.amdhsa_accum_offset 256
		.amdhsa_reserve_vcc 1
		.amdhsa_float_round_mode_32 0
		.amdhsa_float_round_mode_16_64 0
		.amdhsa_float_denorm_mode_32 3
		.amdhsa_float_denorm_mode_16_64 3
		.amdhsa_dx10_clamp 1
		.amdhsa_ieee_mode 1
		.amdhsa_fp16_overflow 0
		.amdhsa_tg_split 0
		.amdhsa_exception_fp_ieee_invalid_op 0
		.amdhsa_exception_fp_denorm_src 0
		.amdhsa_exception_fp_ieee_div_zero 0
		.amdhsa_exception_fp_ieee_overflow 0
		.amdhsa_exception_fp_ieee_underflow 0
		.amdhsa_exception_fp_ieee_inexact 0
		.amdhsa_exception_int_div_zero 0
	.end_amdhsa_kernel

; __global__ void __launch_bounds__(NTHREADS, 2) mega_fwd(Params p) {
.Lfunc_end0:
	.size	_Z8mega_fwd6Params, .Lfunc_end0-_Z8mega_fwd6Params
	.set _Z8mega_fwd6Params.num_vgpr, 256
	.set _Z8mega_fwd6Params.num_agpr, 0
	.set _Z8mega_fwd6Params.numbered_sgpr, 98
	.set _Z8mega_fwd6Params.num_named_barrier, 0
	.set _Z8mega_fwd6Params.private_seg_size, 0
	.set _Z8mega_fwd6Params.uses_vcc, 1
	.set _Z8mega_fwd6Params.uses_flat_scratch, 0
	.set _Z8mega_fwd6Params.has_dyn_sized_stack, 0
	.set _Z8mega_fwd6Params.has_recursion, 0
	.set _Z8mega_fwd6Params.has_indirect_call, 0

; __global__ void __launch_bounds__(NTHREADS, 2) mega_fwd(Params p) {
amdhsa.kernels:
  - .agpr_count:     0
    .args:
      - .offset:         0
        .size:           152
        .value_kind:     by_value
      - .offset:         152
        .size:           4
        .value_kind:     hidden_block_count_x
      - .offset:         156
        .size:           4
        .value_kind:     hidden_block_count_y
      - .offset:         160
        .size:           4
        .value_kind:     hidden_block_count_z
      - .offset:         164
        .size:           2
        .value_kind:     hidden_group_size_x
      - .offset:         166
        .size:           2
        .value_kind:     hidden_group_size_y
      - .offset:         168
        .size:           2
        .value_kind:     hidden_group_size_z
      - .offset:         170
        .size:           2
        .value_kind:     hidden_remainder_x
      - .offset:         172
        .size:           2
        .value_kind:     hidden_remainder_y
      - .offset:         174
        .size:           2
        .value_kind:     hidden_remainder_z
      - .offset:         192
        .size:           8
        .value_kind:     hidden_global_offset_x
      - .offset:         200
        .size:           8
        .value_kind:     hidden_global_offset_y
      - .offset:         208
        .size:           8
        .value_kind:     hidden_global_offset_z
      - .offset:         216
        .size:           2
        .value_kind:     hidden_grid_dims
      - .offset:         240
        .size:           8
        .value_kind:     hidden_multigrid_sync_arg
      - .offset:         272
        .size:           4
        .value_kind:     hidden_dynamic_lds_size
    .group_segment_fixed_size: 0
    .kernarg_segment_align: 8
    .kernarg_segment_size: 408
    .language:       OpenCL C
    .language_version:
      - 2
      - 0
    .max_flat_workgroup_size: 512
    .name:           _Z8mega_fwd6Params
    .private_segment_fixed_size: 0
    .sgpr_count:     104
    .sgpr_spill_count: 63
    .symbol:         _Z8mega_fwd6Params.kd
    .uniform_work_group_size: 1
    .uses_dynamic_stack: false
    .vgpr_count:     256
    .vgpr_spill_count: 0
    .wavefront_size: 64
